# row-max reduction as two interleaved chains in the A and D attention loops
# baseline (speedup 1.0000x reference)
; __device__ __forceinline__ int tid_of(int wave_s) { int l; asm volatile("v_mbcnt_lo_u32_b32 %0, -1, 0\n\tv_mbcnt_hi_u32_b32 %0, -1, %0" : "=v"(l)); return wave_s * 64 + l; }
; __device__ __forceinline__ int crow(int r, int hi) { return (r & 3) + 8 * (r >> 2) + 4 * hi; }
; template <int NQ, int MODE> ...
;     ...
;     for (int r = 0; r < 16; ++r) { const float rl = __builtin_amdgcn_rcpf(RSM ? lacc[r] : li_l[crow(r, hi)]);
; #pragma unroll
;         for (int d = 0; d < 4; ++d) o[d][r] *= rl; }
; __global__ void __launch_bounds__(NTHR, 2) mega_fwd(Args a) {
;     ...
;               const int lane2 = tid_of(wave_s) & 63, r32b = lane2 & 31;
;               const float* scrq = DSCR + ((size_t)(u * 8 + wave_s) * 64) * 64 + lane2; asm volatile("" : "+v"(scrq) :: "memory");
;               const float lam = LAM[lq]; const float* gs = SMV + SM_DS + lq * 128; const float post = 1.f - (0.8f - 0.6f * expf(-0.3f * (float)lq));
;               float gv[4];
; #pragma unroll
;               for (int d0 = 0; d0 < 4; ++d0) gv[d0] = gs[d0 * 32 + r32b] * post;
.LBB0_379:
	s_or_b64 exec, exec, s[34:35]
	v_readlane_b32 s0, v254, 45
	v_readlane_b32 s1, v254, 46
	s_andn2_b64 vcc, exec, s[0:1]
	v_readlane_b32 s40, v255, 32
	v_readlane_b32 s41, v255, 31
	s_waitcnt lgkmcnt(0)
	s_barrier
	s_cbranch_vccz .LBB0_384
.LBB0_380:
	s_mov_b64 s[38:39], s[60:61]
	s_getreg_b32 s0, hwreg(HW_REG_XCC_ID, 0, 4)
	s_waitcnt vmcnt(0)
	v_readlane_b32 s1, v254, 36
	s_waitcnt lgkmcnt(0)
	s_barrier
	v_mbcnt_lo_u32_b32 v0, -1, 0
	v_mbcnt_hi_u32_b32 v0, -1, v0
	s_nop 0
	v_cmp_eq_u32_e32 vcc, s1, v0
	s_and_saveexec_b64 s[34:35], vcc
	s_cbranch_execz .LBB0_908
	v_readlane_b32 s1, v255, 39
	s_waitcnt vmcnt(0) expcnt(0) lgkmcnt(0)
	s_and_b32 s37, s0, 15
	v_mov_b32_e32 v0, s1
	ds_read_b32 v2, v0
	v_readlane_b32 s1, v255, 40
	s_waitcnt lgkmcnt(0)
	v_cmp_ne_u32_e32 vcc, 0, v2
	v_mov_b32_e32 v0, s1
	ds_read_b32 v0, v0
	s_cbranch_vccnz .LBB0_879
	s_add_u32 s0, s38, 0x10200
	s_addc_u32 s1, s39, 0
	s_add_u32 s4, s38, 0x10400
	s_addc_u32 s5, s39, 0
	s_add_u32 s6, s38, 0x10500
	s_addc_u32 s7, s39, 0
	s_add_u32 s8, s38, 0x10600
	s_addc_u32 s9, s39, 0
	s_add_u32 s10, s38, 0x10700
	s_addc_u32 s11, s39, 0
	s_add_u32 s12, s38, 0x10800
	s_addc_u32 s13, s39, 0
	s_add_u32 s14, s38, 0x10900
	s_addc_u32 s15, s39, 0
	s_add_u32 s16, s38, 0x10a00
	s_addc_u32 s17, s39, 0
	s_add_u32 s18, s38, 0x10b00
	s_addc_u32 s19, s39, 0
	s_add_u32 s20, s38, 0x10c00
	s_addc_u32 s21, s39, 0
	s_add_u32 s22, s38, 0x10d00
	s_addc_u32 s23, s39, 0
	s_add_u32 s24, s38, 0x10e00
	s_addc_u32 s25, s39, 0
	s_add_u32 s26, s38, 0x10f00
	s_addc_u32 s27, s39, 0
	s_add_u32 s28, s38, 0x11000
	s_addc_u32 s29, s39, 0
	s_add_u32 s30, s38, 0x11100
	s_addc_u32 s31, s39, 0
	s_add_u32 s56, s38, 0x11200
	s_addc_u32 s57, s39, 0
	s_add_u32 s78, s38, 0x11300
	s_addc_u32 s79, s39, 0
	s_mov_b32 s85, 1
	s_mov_b64 s[66:67], 0
	s_branch .LBB0_869
.LBB0_383:
	s_or_b64 exec, exec, s[0:1]
	v_rcp_f32_e32 v0, v80
	s_waitcnt lgkmcnt(0)
	s_ashr_i32 s31, s30, 31
	s_lshl_b64 s[0:1], s[30:31], 2
	v_mul_f32_e32 v4, v0, v64
	v_mul_f32_e32 v6, v0, v48
	v_mul_f32_e32 v8, v0, v32
	s_nop 2
	v_mul_f32_e32 v118, v0, v16
	v_rcp_f32_e32 v0, v81
	s_add_u32 s0, s28, s0
	s_addc_u32 s1, s29, s1
	v_mov_b64_e32 v[14:15], s[0:1]
	v_mul_f32_e32 v116, v0, v65
	v_mul_f32_e32 v117, v0, v49
	v_mul_f32_e32 v115, v0, v33
	v_mul_f32_e32 v114, v0, v17
	v_rcp_f32_e32 v0, v82
	s_mov_b32 s4, 0x3fb8aa3b
	s_lshl_b32 s0, s30, 7
	s_ashr_i32 s1, s0, 31
	v_mul_f32_e32 v112, v0, v66
	v_mul_f32_e32 v113, v0, v50
	v_mul_f32_e32 v33, v0, v34
	v_mul_f32_e32 v32, v0, v18
	v_rcp_f32_e32 v0, v83
	s_lshl_b64 s[0:1], s[0:1], 2
	s_add_u32 s0, s28, s0
	s_addc_u32 s1, s29, s1
	v_mul_f32_e32 v110, v0, v67
	v_mul_f32_e32 v111, v0, v51
	v_mul_f32_e32 v109, v0, v35
	v_mul_f32_e32 v108, v0, v19
	v_rcp_f32_e32 v0, v84
	s_add_i32 s41, s41, s62
	v_mul_f32_e32 v107, v0, v68
	v_mul_f32_e32 v106, v0, v52
	v_mul_f32_e32 v105, v0, v36
	v_mul_f32_e32 v104, v0, v20
	v_rcp_f32_e32 v0, v85
	s_nop 0
	v_mul_f32_e32 v102, v0, v69
	v_mul_f32_e32 v103, v0, v53
	v_mul_f32_e32 v101, v0, v37
	v_mul_f32_e32 v100, v0, v21
	v_rcp_f32_e32 v0, v86
	s_nop 0
	v_mul_f32_e32 v98, v0, v70
	v_mul_f32_e32 v99, v0, v54
	v_mul_f32_e32 v97, v0, v38
	v_mul_f32_e32 v96, v0, v22
	v_rcp_f32_e32 v0, v87
	s_nop 0
	v_mul_f32_e32 v85, v0, v71
	v_mul_f32_e32 v86, v0, v55
	v_mul_f32_e32 v84, v0, v39
	v_mul_f32_e32 v71, v0, v23
	v_rcp_f32_e32 v0, v88
	s_nop 0
	v_mul_f32_e32 v83, v0, v72
	v_mul_f32_e32 v82, v0, v56
	v_mul_f32_e32 v81, v0, v40
	v_mul_f32_e32 v80, v0, v24
	v_rcp_f32_e32 v0, v89
	s_nop 0
	v_mul_f32_e32 v69, v0, v73
	v_mul_f32_e32 v70, v0, v57
	v_mul_f32_e32 v68, v0, v41
	v_mul_f32_e32 v67, v0, v25
	v_rcp_f32_e32 v0, v90
	s_nop 0
	v_mul_f32_e32 v65, v0, v74
	v_mul_f32_e32 v66, v0, v58
	v_mul_f32_e32 v64, v0, v42
	v_mul_f32_e32 v58, v0, v26
	v_rcp_f32_e32 v0, v91
	s_nop 0
	v_mul_f32_e32 v52, v0, v75
	v_mul_f32_e32 v53, v0, v59
	v_mul_f32_e32 v51, v0, v43
	v_mul_f32_e32 v50, v0, v27
	v_rcp_f32_e32 v0, v92
	s_nop 0
	v_mul_f32_e32 v49, v0, v76
	v_mul_f32_e32 v48, v0, v60
	v_mul_f32_e32 v43, v0, v44
	v_mul_f32_e32 v42, v0, v28
	v_rcp_f32_e32 v0, v93
	s_nop 0
	v_mul_f32_e32 v36, v0, v77
	v_mul_f32_e32 v37, v0, v61
	v_mul_f32_e32 v35, v0, v45
	v_mul_f32_e32 v34, v0, v29
	v_rcp_f32_e32 v0, v94
	s_nop 0
	v_mul_f32_e32 v28, v0, v78
	v_mul_f32_e32 v29, v0, v62
	v_mul_f32_e32 v27, v0, v46
	v_mul_f32_e32 v26, v0, v30
	v_rcp_f32_e32 v0, v95
	s_nop 0
	v_mul_f32_e32 v12, v0, v79
	v_mul_f32_e32 v13, v0, v63
	v_mul_f32_e32 v11, v0, v47
	v_mul_f32_e32 v10, v0, v31
	v_mbcnt_lo_u32_b32 v0, -1, 0
	v_mbcnt_hi_u32_b32 v0, -1, v0
	s_nop 0
	v_and_b32_e32 v2, 63, v0
	v_and_b32_e32 v5, 31, v0
	v_lshlrev_b32_e32 v0, 2, v2
	v_lshl_add_u64 v[2:3], s[20:21], 0, v[0:1]
	v_cvt_f32_i32_e32 v0, s30
	flat_load_dword v17, v[14:15]
	v_mul_f32_e32 v0, 0xbe99999a, v0
	v_mul_f32_e32 v7, 0x3fb8aa3b, v0
	v_fma_f32 v9, v0, s4, -v7
	v_rndne_f32_e32 v14, v7
	v_fmac_f32_e32 v9, 0x32a5705f, v0
	v_sub_f32_e32 v7, v7, v14
	v_add_f32_e32 v7, v7, v9
	v_exp_f32_e32 v7, v7
	v_cvt_i32_f32_e32 v9, v14
	s_mov_b32 s4, 0xc2ce8ed0
	v_cmp_ngt_f32_e32 vcc, s4, v0
	s_mov_b32 s4, 0x42b17218
	v_ldexp_f32 v7, v7, v9
	v_cndmask_b32_e32 v7, 0, v7, vcc
	v_cmp_nlt_f32_e32 vcc, s4, v0
	v_mov_b32_e32 v0, 0x7f800000
	s_nop 0
	v_cndmask_b32_e32 v0, v0, v7, vcc
	v_mov_b32_e32 v7, 0xbf4ccccd
	v_fmamk_f32 v0, v0, 0x3f19999a, v7
	v_add_f32_e32 v7, 1.0, v0
	v_lshlrev_b32_e32 v0, 2, v5
	v_lshl_add_u64 v[14:15], s[0:1], 0, v[0:1]
	s_mov_b64 s[0:1], 0x2a800
	v_lshl_add_u64 v[18:19], v[14:15], 0, s[0:1]
	s_mov_b32 s0, 0x2a000
	v_add_co_u32_e32 v14, vcc, s0, v14
	flat_load_dword v5, v[18:19] offset:128
	s_nop 0
	v_addc_co_u32_e32 v15, vcc, 0, v15, vcc
	flat_load_dword v0, v[14:15] offset:2048
	s_movk_i32 s0, 0x1000
	s_waitcnt vmcnt(0) lgkmcnt(0)
; __global__ void __launch_bounds__(NTHR, 2) mega_fwd(Args a) {
;     ...
;               for (int r = 0; r < 16; ++r) { float ss = 0.f;
; #pragma unroll
;                   for (int d0 = 0; d0 < 4; ++d0) { const float dv = scrq[(d0 * 16 + r) * 64] - lam * o[d0][r]; o[d0][r] = dv; ss += dv * dv; }
;                   ss = half_sum(ss);
;                   const float rstd = 1.0f / sqrtf(ss * (1.f / 128.f) + EPS);
; #pragma unroll
;                   for (int d0 = 0; d0 < 4; ++d0) o[d0][r] *= rstd * gv[d0];
;                   if ((r & 3) == 3) asm volatile("" ::: "memory"); }
	v_mul_f32_e32 v14, v7, v5
	flat_load_dword v5, v[18:19] offset:256
	v_mul_f32_e32 v0, v7, v0
	s_waitcnt vmcnt(0) lgkmcnt(0)
	v_mul_f32_e32 v15, v7, v5
	flat_load_dword v5, v[18:19] offset:384
	s_waitcnt vmcnt(0) lgkmcnt(0)
	v_mul_f32_e32 v16, v7, v5
	flat_load_dword v5, v[2:3]
	s_waitcnt vmcnt(0) lgkmcnt(0)
	v_fma_f32 v18, -v17, v4, v5
	v_add_co_u32_e32 v4, vcc, s0, v2
	s_movk_i32 s0, 0x2000
	s_nop 0
	v_addc_co_u32_e32 v5, vcc, 0, v3, vcc
	flat_load_dword v7, v[4:5]
	s_waitcnt vmcnt(0) lgkmcnt(0)
	v_fma_f32 v19, -v17, v6, v7
	v_add_co_u32_e32 v6, vcc, s0, v2
	s_movk_i32 s0, 0x3000
	s_nop 0
	v_addc_co_u32_e32 v7, vcc, 0, v3, vcc
	flat_load_dword v9, v[6:7]
	v_mul_f32_e32 v20, v19, v19
	v_fmac_f32_e32 v20, v18, v18
	s_waitcnt vmcnt(0) lgkmcnt(0)
	v_fma_f32 v22, -v17, v8, v9
	v_add_co_u32_e32 v8, vcc, s0, v2
	v_fmac_f32_e32 v20, v22, v22
	s_nop 0
	v_addc_co_u32_e32 v9, vcc, 0, v3, vcc
	flat_load_dword v21, v[8:9]
	s_waitcnt vmcnt(0) lgkmcnt(0)
	v_fma_f32 v23, -v17, v118, v21
	v_fmac_f32_e32 v20, v23, v23
	ds_swizzle_b32 v21, v20 offset:swizzle(SWAP,1)
	s_waitcnt lgkmcnt(0)
	v_add_f32_e32 v20, v20, v21
	ds_swizzle_b32 v21, v20 offset:swizzle(SWAP,2)
	s_waitcnt lgkmcnt(0)
	v_add_f32_e32 v20, v20, v21
	ds_swizzle_b32 v21, v20 offset:swizzle(SWAP,4)
	s_waitcnt lgkmcnt(0)
	v_add_f32_e32 v20, v20, v21
	ds_swizzle_b32 v21, v20 offset:swizzle(SWAP,8)
	s_waitcnt lgkmcnt(0)
	v_add_f32_e32 v20, v20, v21
	ds_swizzle_b32 v21, v20 offset:swizzle(SWAP,16)
	s_waitcnt lgkmcnt(0)
	v_add_f32_e32 v20, v20, v21
	v_fmamk_f32 v20, v20, 0x3c000000, v218
	v_cmp_gt_f32_e32 vcc, s68, v20
	v_mul_f32_e32 v21, 0x4f800000, v20
	s_nop 0
	v_cndmask_b32_e32 v20, v20, v21, vcc
	v_sqrt_f32_e32 v21, v20
	s_nop 0
	v_add_u32_e32 v24, -1, v21
	v_fma_f32 v25, -v24, v21, v20
	v_cmp_ge_f32_e64 s[0:1], 0, v25
	v_add_u32_e32 v25, 1, v21
	s_nop 0
	v_cndmask_b32_e64 v24, v21, v24, s[0:1]
	v_fma_f32 v21, -v25, v21, v20
	v_cmp_lt_f32_e64 s[0:1], 0, v21
	s_nop 1
	v_cndmask_b32_e64 v21, v24, v25, s[0:1]
	v_mul_f32_e32 v24, 0x37800000, v21
	v_cndmask_b32_e32 v21, v21, v24, vcc
	v_cmp_class_f32_e32 vcc, v20, v219
	s_nop 1
	v_cndmask_b32_e32 v20, v21, v20, vcc
	v_div_scale_f32 v21, s[0:1], v20, v20, 1.0
	v_rcp_f32_e32 v24, v21
	s_nop 0
	v_fma_f32 v25, -v21, v24, 1.0
	v_fmac_f32_e32 v24, v25, v24
	v_div_scale_f32 v25, vcc, 1.0, v20, 1.0
	v_mul_f32_e32 v30, v25, v24
	v_fma_f32 v31, -v21, v30, v25
	v_fmac_f32_e32 v30, v31, v24
	v_fma_f32 v21, -v21, v30, v25
	v_div_fmas_f32 v21, v21, v24, v30
	v_div_fixup_f32 v24, v21, v20, 1.0
	v_mul_f32_e32 v20, v24, v0
	v_mul_f32_e32 v21, v20, v18
	v_mul_f32_e32 v18, v24, v14
	v_mul_f32_e32 v20, v18, v19
	v_mul_f32_e32 v18, v24, v15
	v_mul_f32_e32 v19, v18, v22
	v_mul_f32_e32 v18, v24, v16
	v_mul_f32_e32 v18, v18, v23
	flat_load_dword v22, v[8:9] offset:256
	flat_load_dword v23, v[6:7] offset:256
	flat_load_dword v24, v[4:5] offset:256
	flat_load_dword v25, v[2:3] offset:256
	s_waitcnt vmcnt(0) lgkmcnt(0)
	v_fma_f32 v22, -v17, v114, v22
	v_fma_f32 v23, -v17, v115, v23
	v_fma_f32 v24, -v17, v117, v24
	v_fma_f32 v25, -v17, v116, v25
	v_mul_f32_e32 v30, v24, v24
	v_fmac_f32_e32 v30, v25, v25
	v_fmac_f32_e32 v30, v23, v23
	v_fmac_f32_e32 v30, v22, v22
	ds_swizzle_b32 v31, v30 offset:swizzle(SWAP,1)
	s_waitcnt lgkmcnt(0)
	v_add_f32_e32 v30, v30, v31
	ds_swizzle_b32 v31, v30 offset:swizzle(SWAP,2)
	s_waitcnt lgkmcnt(0)
	v_add_f32_e32 v30, v30, v31
	ds_swizzle_b32 v31, v30 offset:swizzle(SWAP,4)
	s_waitcnt lgkmcnt(0)
	v_add_f32_e32 v30, v30, v31
	ds_swizzle_b32 v31, v30 offset:swizzle(SWAP,8)
	s_waitcnt lgkmcnt(0)
	v_add_f32_e32 v30, v30, v31
	ds_swizzle_b32 v31, v30 offset:swizzle(SWAP,16)
	s_waitcnt lgkmcnt(0)
	v_add_f32_e32 v30, v30, v31
	v_fmamk_f32 v30, v30, 0x3c000000, v218
	v_cmp_gt_f32_e32 vcc, s68, v30
	v_mul_f32_e32 v31, 0x4f800000, v30
	s_nop 0
	v_cndmask_b32_e32 v30, v30, v31, vcc
	v_sqrt_f32_e32 v31, v30
	s_nop 0
	v_add_u32_e32 v38, -1, v31
	v_fma_f32 v39, -v38, v31, v30
	v_cmp_ge_f32_e64 s[0:1], 0, v39
	v_add_u32_e32 v39, 1, v31
	s_nop 0
	v_cndmask_b32_e64 v38, v31, v38, s[0:1]
	v_fma_f32 v31, -v39, v31, v30
	v_cmp_lt_f32_e64 s[0:1], 0, v31
	s_nop 1
	v_cndmask_b32_e64 v31, v38, v39, s[0:1]
	v_mul_f32_e32 v38, 0x37800000, v31
	v_cndmask_b32_e32 v31, v31, v38, vcc
	v_cmp_class_f32_e32 vcc, v30, v219
	s_nop 1
	v_cndmask_b32_e32 v30, v31, v30, vcc
	v_div_scale_f32 v31, s[0:1], v30, v30, 1.0
	v_rcp_f32_e32 v38, v31
	s_nop 0
	v_fma_f32 v39, -v31, v38, 1.0
	v_fmac_f32_e32 v38, v39, v38
	v_div_scale_f32 v39, vcc, 1.0, v30, 1.0
	v_mul_f32_e32 v40, v39, v38
	v_fma_f32 v41, -v31, v40, v39
	v_fmac_f32_e32 v40, v41, v38
	v_fma_f32 v31, -v31, v40, v39
	v_div_fmas_f32 v31, v31, v38, v40
	v_div_fixup_f32 v30, v31, v30, 1.0
	v_mul_f32_e32 v31, v30, v0
	v_mul_f32_e32 v25, v31, v25
	v_mul_f32_e32 v31, v30, v14
	v_mul_f32_e32 v24, v31, v24
	v_mul_f32_e32 v31, v30, v15
	v_mul_f32_e32 v30, v30, v16
	v_mul_f32_e32 v23, v31, v23
	v_mul_f32_e32 v22, v30, v22
	flat_load_dword v30, v[8:9] offset:512
	flat_load_dword v31, v[6:7] offset:512
	flat_load_dword v38, v[4:5] offset:512
	flat_load_dword v39, v[2:3] offset:512
	s_waitcnt vmcnt(0) lgkmcnt(0)
	v_fma_f32 v30, -v17, v32, v30
	v_fma_f32 v31, -v17, v33, v31
	v_fma_f32 v38, -v17, v113, v38
	v_fma_f32 v39, -v17, v112, v39
	v_mul_f32_e32 v40, v38, v38
	v_fmac_f32_e32 v40, v39, v39
	v_fmac_f32_e32 v40, v31, v31
	v_fmac_f32_e32 v40, v30, v30
	ds_swizzle_b32 v32, v40 offset:swizzle(SWAP,1)
	s_waitcnt lgkmcnt(0)
	v_add_f32_e32 v32, v40, v32
	ds_swizzle_b32 v33, v32 offset:swizzle(SWAP,2)
	s_waitcnt lgkmcnt(0)
	v_add_f32_e32 v32, v32, v33
	ds_swizzle_b32 v33, v32 offset:swizzle(SWAP,4)
	s_waitcnt lgkmcnt(0)
; __global__ void __launch_bounds__(NTHR, 2) mega_fwd(Args a) {
;     ...
;               for (int r = 0; r < 16; ++r) { float ss = 0.f;
; #pragma unroll
;                   for (int d0 = 0; d0 < 4; ++d0) { const float dv = scrq[(d0 * 16 + r) * 64] - lam * o[d0][r]; o[d0][r] = dv; ss += dv * dv; }
;                   ss = half_sum(ss);
;                   const float rstd = 1.0f / sqrtf(ss * (1.f / 128.f) + EPS);
; #pragma unroll
;                   for (int d0 = 0; d0 < 4; ++d0) o[d0][r] *= rstd * gv[d0];
;                   if ((r & 3) == 3) asm volatile("" ::: "memory"); }
	v_add_f32_e32 v32, v32, v33
	ds_swizzle_b32 v33, v32 offset:swizzle(SWAP,8)
	s_waitcnt lgkmcnt(0)
	v_add_f32_e32 v32, v32, v33
	ds_swizzle_b32 v33, v32 offset:swizzle(SWAP,16)
	s_waitcnt lgkmcnt(0)
	v_add_f32_e32 v32, v32, v33
	v_fmamk_f32 v32, v32, 0x3c000000, v218
	v_cmp_gt_f32_e32 vcc, s68, v32
	v_mul_f32_e32 v33, 0x4f800000, v32
	s_nop 0
	v_cndmask_b32_e32 v32, v32, v33, vcc
	v_sqrt_f32_e32 v33, v32
	s_nop 0
	v_add_u32_e32 v40, -1, v33
	v_fma_f32 v41, -v40, v33, v32
	v_cmp_ge_f32_e64 s[0:1], 0, v41
	v_add_u32_e32 v41, 1, v33
	s_nop 0
	v_cndmask_b32_e64 v40, v33, v40, s[0:1]
	v_fma_f32 v33, -v41, v33, v32
	v_cmp_lt_f32_e64 s[0:1], 0, v33
	s_nop 1
	v_cndmask_b32_e64 v33, v40, v41, s[0:1]
	v_mul_f32_e32 v40, 0x37800000, v33
	v_cndmask_b32_e32 v33, v33, v40, vcc
	v_cmp_class_f32_e32 vcc, v32, v219
	s_nop 1
	v_cndmask_b32_e32 v32, v33, v32, vcc
	v_div_scale_f32 v33, s[0:1], v32, v32, 1.0
	v_rcp_f32_e32 v40, v33
	s_nop 0
	v_fma_f32 v41, -v33, v40, 1.0
	v_fmac_f32_e32 v40, v41, v40
	v_div_scale_f32 v41, vcc, 1.0, v32, 1.0
	v_mul_f32_e32 v44, v41, v40
	v_fma_f32 v45, -v33, v44, v41
	v_fmac_f32_e32 v44, v45, v40
	v_fma_f32 v33, -v33, v44, v41
	v_div_fmas_f32 v33, v33, v40, v44
	v_div_fixup_f32 v40, v33, v32, 1.0
	v_mul_f32_e32 v32, v40, v0
	v_mul_f32_e32 v33, v32, v39
	v_mul_f32_e32 v32, v40, v14
	v_mul_f32_e32 v32, v32, v38
	v_mul_f32_e32 v38, v40, v15
	v_mul_f32_e32 v31, v38, v31
	v_mul_f32_e32 v38, v40, v16
	v_mul_f32_e32 v30, v38, v30
	flat_load_dword v38, v[8:9] offset:768
	flat_load_dword v39, v[6:7] offset:768
	flat_load_dword v40, v[4:5] offset:768
	flat_load_dword v41, v[2:3] offset:768
	s_waitcnt vmcnt(0) lgkmcnt(0)
	v_fma_f32 v38, -v17, v108, v38
	v_fma_f32 v39, -v17, v109, v39
	v_fma_f32 v40, -v17, v111, v40
	v_fma_f32 v41, -v17, v110, v41
	v_mul_f32_e32 v44, v40, v40
	v_fmac_f32_e32 v44, v41, v41
	v_fmac_f32_e32 v44, v39, v39
	v_fmac_f32_e32 v44, v38, v38
	ds_swizzle_b32 v45, v44 offset:swizzle(SWAP,1)
	s_waitcnt lgkmcnt(0)
	v_add_f32_e32 v44, v44, v45
	ds_swizzle_b32 v45, v44 offset:swizzle(SWAP,2)
	s_waitcnt lgkmcnt(0)
	v_add_f32_e32 v44, v44, v45
	ds_swizzle_b32 v45, v44 offset:swizzle(SWAP,4)
	s_waitcnt lgkmcnt(0)
	v_add_f32_e32 v44, v44, v45
	ds_swizzle_b32 v45, v44 offset:swizzle(SWAP,8)
	s_waitcnt lgkmcnt(0)
	v_add_f32_e32 v44, v44, v45
	ds_swizzle_b32 v45, v44 offset:swizzle(SWAP,16)
	s_waitcnt lgkmcnt(0)
	v_add_f32_e32 v44, v44, v45
	v_fmamk_f32 v44, v44, 0x3c000000, v218
	v_cmp_gt_f32_e32 vcc, s68, v44
	v_mul_f32_e32 v45, 0x4f800000, v44
	s_nop 0
	v_cndmask_b32_e32 v44, v44, v45, vcc
	v_sqrt_f32_e32 v45, v44
	s_nop 0
	v_add_u32_e32 v46, -1, v45
	v_fma_f32 v47, -v46, v45, v44
	v_cmp_ge_f32_e64 s[0:1], 0, v47
	v_add_u32_e32 v47, 1, v45
	s_nop 0
	v_cndmask_b32_e64 v46, v45, v46, s[0:1]
	v_fma_f32 v45, -v47, v45, v44
	v_cmp_lt_f32_e64 s[0:1], 0, v45
	s_nop 1
	v_cndmask_b32_e64 v45, v46, v47, s[0:1]
	v_mul_f32_e32 v46, 0x37800000, v45
	v_cndmask_b32_e32 v45, v45, v46, vcc
	v_cmp_class_f32_e32 vcc, v44, v219
	s_nop 1
	v_cndmask_b32_e32 v44, v45, v44, vcc
	v_div_scale_f32 v45, s[0:1], v44, v44, 1.0
	v_rcp_f32_e32 v46, v45
	s_nop 0
	v_fma_f32 v47, -v45, v46, 1.0
	v_fmac_f32_e32 v46, v47, v46
	v_div_scale_f32 v47, vcc, 1.0, v44, 1.0
	v_mul_f32_e32 v54, v47, v46
	v_fma_f32 v55, -v45, v54, v47
	v_fmac_f32_e32 v54, v55, v46
	v_fma_f32 v45, -v45, v54, v47
	v_div_fmas_f32 v45, v45, v46, v54
	v_div_fixup_f32 v44, v45, v44, 1.0
	v_mul_f32_e32 v45, v44, v0
	v_mul_f32_e32 v41, v45, v41
	v_mul_f32_e32 v45, v44, v14
	v_mul_f32_e32 v40, v45, v40
	v_mul_f32_e32 v45, v44, v15
	v_mul_f32_e32 v44, v44, v16
	v_mul_f32_e32 v39, v45, v39
	v_mul_f32_e32 v38, v44, v38
	flat_load_dword v44, v[2:3] offset:1024
	flat_load_dword v45, v[4:5] offset:1024
	flat_load_dword v47, v[6:7] offset:1024
	s_waitcnt vmcnt(0) lgkmcnt(0)
	v_fma_f32 v44, -v17, v107, v44
	v_fma_f32 v45, -v17, v106, v45
	v_fma_f32 v54, -v17, v105, v47
	flat_load_dword v47, v[8:9] offset:1024
	v_mul_f32_e32 v46, v45, v45
	v_fmac_f32_e32 v46, v44, v44
	v_fmac_f32_e32 v46, v54, v54
	s_waitcnt vmcnt(0) lgkmcnt(0)
	v_fma_f32 v55, -v17, v104, v47
	v_fmac_f32_e32 v46, v55, v55
	ds_swizzle_b32 v47, v46 offset:swizzle(SWAP,1)
	s_waitcnt lgkmcnt(0)
	v_add_f32_e32 v46, v46, v47
	ds_swizzle_b32 v47, v46 offset:swizzle(SWAP,2)
	s_waitcnt lgkmcnt(0)
	v_add_f32_e32 v46, v46, v47
	ds_swizzle_b32 v47, v46 offset:swizzle(SWAP,4)
	s_waitcnt lgkmcnt(0)
	v_add_f32_e32 v46, v46, v47
	ds_swizzle_b32 v47, v46 offset:swizzle(SWAP,8)
	s_waitcnt lgkmcnt(0)
	v_add_f32_e32 v46, v46, v47
	ds_swizzle_b32 v47, v46 offset:swizzle(SWAP,16)
	s_waitcnt lgkmcnt(0)
	v_add_f32_e32 v46, v46, v47
	v_fmamk_f32 v46, v46, 0x3c000000, v218
	v_cmp_gt_f32_e32 vcc, s68, v46
	v_mul_f32_e32 v47, 0x4f800000, v46
	s_nop 0
	v_cndmask_b32_e32 v46, v46, v47, vcc
	v_sqrt_f32_e32 v47, v46
	s_nop 0
	v_add_u32_e32 v56, -1, v47
	v_fma_f32 v57, -v56, v47, v46
	v_cmp_ge_f32_e64 s[0:1], 0, v57
	v_add_u32_e32 v57, 1, v47
	s_nop 0
	v_cndmask_b32_e64 v56, v47, v56, s[0:1]
	v_fma_f32 v47, -v57, v47, v46
	v_cmp_lt_f32_e64 s[0:1], 0, v47
	s_nop 1
	v_cndmask_b32_e64 v47, v56, v57, s[0:1]
	v_mul_f32_e32 v56, 0x37800000, v47
	v_cndmask_b32_e32 v47, v47, v56, vcc
	v_cmp_class_f32_e32 vcc, v46, v219
	s_nop 1
	v_cndmask_b32_e32 v46, v47, v46, vcc
	v_div_scale_f32 v47, s[0:1], v46, v46, 1.0
	v_rcp_f32_e32 v56, v47
	s_nop 0
	v_fma_f32 v57, -v47, v56, 1.0
	v_fmac_f32_e32 v56, v57, v56
	v_div_scale_f32 v57, vcc, 1.0, v46, 1.0
	v_mul_f32_e32 v59, v57, v56
	v_fma_f32 v60, -v47, v59, v57
	v_fmac_f32_e32 v59, v60, v56
	v_fma_f32 v47, -v47, v59, v57
	v_div_fmas_f32 v47, v47, v56, v59
	v_div_fixup_f32 v56, v47, v46, 1.0
	v_mul_f32_e32 v46, v56, v0
	v_mul_f32_e32 v47, v46, v44
	v_mul_f32_e32 v44, v56, v14
	v_mul_f32_e32 v46, v44, v45
	v_mul_f32_e32 v44, v56, v15
	v_mul_f32_e32 v45, v44, v54
	v_mul_f32_e32 v44, v56, v16
	v_mul_f32_e32 v44, v44, v55
	flat_load_dword v54, v[8:9] offset:1280
	flat_load_dword v55, v[6:7] offset:1280
	flat_load_dword v56, v[4:5] offset:1280
	flat_load_dword v57, v[2:3] offset:1280
	s_waitcnt vmcnt(0) lgkmcnt(0)
; __global__ void __launch_bounds__(NTHR, 2) mega_fwd(Args a) {
;     ...
;               for (int r = 0; r < 16; ++r) { float ss = 0.f;
; #pragma unroll
;                   for (int d0 = 0; d0 < 4; ++d0) { const float dv = scrq[(d0 * 16 + r) * 64] - lam * o[d0][r]; o[d0][r] = dv; ss += dv * dv; }
;                   ss = half_sum(ss);
;                   const float rstd = 1.0f / sqrtf(ss * (1.f / 128.f) + EPS);
; #pragma unroll
;                   for (int d0 = 0; d0 < 4; ++d0) o[d0][r] *= rstd * gv[d0];
;                   if ((r & 3) == 3) asm volatile("" ::: "memory"); }
	v_fma_f32 v54, -v17, v100, v54
	v_fma_f32 v55, -v17, v101, v55
	v_fma_f32 v56, -v17, v103, v56
	v_fma_f32 v57, -v17, v102, v57
	v_mul_f32_e32 v59, v56, v56
	v_fmac_f32_e32 v59, v57, v57
	v_fmac_f32_e32 v59, v55, v55
	v_fmac_f32_e32 v59, v54, v54
	ds_swizzle_b32 v60, v59 offset:swizzle(SWAP,1)
	s_waitcnt lgkmcnt(0)
	v_add_f32_e32 v59, v59, v60
	ds_swizzle_b32 v60, v59 offset:swizzle(SWAP,2)
	s_waitcnt lgkmcnt(0)
	v_add_f32_e32 v59, v59, v60
	ds_swizzle_b32 v60, v59 offset:swizzle(SWAP,4)
	s_waitcnt lgkmcnt(0)
	v_add_f32_e32 v59, v59, v60
	ds_swizzle_b32 v60, v59 offset:swizzle(SWAP,8)
	s_waitcnt lgkmcnt(0)
	v_add_f32_e32 v59, v59, v60
	ds_swizzle_b32 v60, v59 offset:swizzle(SWAP,16)
	s_waitcnt lgkmcnt(0)
	v_add_f32_e32 v59, v59, v60
	v_fmamk_f32 v59, v59, 0x3c000000, v218
	v_cmp_gt_f32_e32 vcc, s68, v59
	v_mul_f32_e32 v60, 0x4f800000, v59
	s_nop 0
	v_cndmask_b32_e32 v59, v59, v60, vcc
	v_sqrt_f32_e32 v60, v59
	s_nop 0
	v_add_u32_e32 v61, -1, v60
	v_fma_f32 v62, -v61, v60, v59
	v_cmp_ge_f32_e64 s[0:1], 0, v62
	v_add_u32_e32 v62, 1, v60
	s_nop 0
	v_cndmask_b32_e64 v61, v60, v61, s[0:1]
	v_fma_f32 v60, -v62, v60, v59
	v_cmp_lt_f32_e64 s[0:1], 0, v60
	s_nop 1
	v_cndmask_b32_e64 v60, v61, v62, s[0:1]
	v_mul_f32_e32 v61, 0x37800000, v60
	v_cndmask_b32_e32 v60, v60, v61, vcc
	v_cmp_class_f32_e32 vcc, v59, v219
	s_nop 1
	v_cndmask_b32_e32 v59, v60, v59, vcc
	v_div_scale_f32 v60, s[0:1], v59, v59, 1.0
	v_rcp_f32_e32 v61, v60
	s_nop 0
	v_fma_f32 v62, -v60, v61, 1.0
	v_fmac_f32_e32 v61, v62, v61
	v_div_scale_f32 v62, vcc, 1.0, v59, 1.0
	v_mul_f32_e32 v63, v62, v61
	v_fma_f32 v72, -v60, v63, v62
	v_fmac_f32_e32 v63, v72, v61
	v_fma_f32 v60, -v60, v63, v62
	v_div_fmas_f32 v60, v60, v61, v63
	v_div_fixup_f32 v59, v60, v59, 1.0
	v_mul_f32_e32 v60, v59, v0
	v_mul_f32_e32 v57, v60, v57
	v_mul_f32_e32 v60, v59, v14
	v_mul_f32_e32 v56, v60, v56
	v_mul_f32_e32 v60, v59, v15
	v_mul_f32_e32 v59, v59, v16
	v_mul_f32_e32 v55, v60, v55
	v_mul_f32_e32 v54, v59, v54
	flat_load_dword v59, v[8:9] offset:1536
	flat_load_dword v60, v[6:7] offset:1536
	flat_load_dword v61, v[4:5] offset:1536
	flat_load_dword v62, v[2:3] offset:1536
	s_waitcnt vmcnt(0) lgkmcnt(0)
	v_fma_f32 v59, -v17, v96, v59
	v_fma_f32 v60, -v17, v97, v60
	v_fma_f32 v61, -v17, v99, v61
	v_fma_f32 v62, -v17, v98, v62
	v_mul_f32_e32 v63, v61, v61
	v_fmac_f32_e32 v63, v62, v62
	v_fmac_f32_e32 v63, v60, v60
	v_fmac_f32_e32 v63, v59, v59
	ds_swizzle_b32 v72, v63 offset:swizzle(SWAP,1)
	s_waitcnt lgkmcnt(0)
	v_add_f32_e32 v63, v63, v72
	ds_swizzle_b32 v72, v63 offset:swizzle(SWAP,2)
	s_waitcnt lgkmcnt(0)
	v_add_f32_e32 v63, v63, v72
	ds_swizzle_b32 v72, v63 offset:swizzle(SWAP,4)
	s_waitcnt lgkmcnt(0)
	v_add_f32_e32 v63, v63, v72
	ds_swizzle_b32 v72, v63 offset:swizzle(SWAP,8)
	s_waitcnt lgkmcnt(0)
	v_add_f32_e32 v63, v63, v72
	ds_swizzle_b32 v72, v63 offset:swizzle(SWAP,16)
	s_waitcnt lgkmcnt(0)
	v_add_f32_e32 v63, v63, v72
	v_fmamk_f32 v63, v63, 0x3c000000, v218
	v_cmp_gt_f32_e32 vcc, s68, v63
	v_mul_f32_e32 v72, 0x4f800000, v63
	s_nop 0
	v_cndmask_b32_e32 v63, v63, v72, vcc
	v_sqrt_f32_e32 v72, v63
	s_nop 0
	v_add_u32_e32 v73, -1, v72
	v_fma_f32 v74, -v73, v72, v63
	v_cmp_ge_f32_e64 s[0:1], 0, v74
	v_add_u32_e32 v74, 1, v72
	s_nop 0
	v_cndmask_b32_e64 v73, v72, v73, s[0:1]
	v_fma_f32 v72, -v74, v72, v63
	v_cmp_lt_f32_e64 s[0:1], 0, v72
	s_nop 1
	v_cndmask_b32_e64 v72, v73, v74, s[0:1]
	v_mul_f32_e32 v73, 0x37800000, v72
	v_cndmask_b32_e32 v72, v72, v73, vcc
	v_cmp_class_f32_e32 vcc, v63, v219
	s_nop 1
	v_cndmask_b32_e32 v63, v72, v63, vcc
	v_div_scale_f32 v72, s[0:1], v63, v63, 1.0
	v_rcp_f32_e32 v73, v72
	s_nop 0
	v_fma_f32 v74, -v72, v73, 1.0
	v_fmac_f32_e32 v73, v74, v73
	v_div_scale_f32 v74, vcc, 1.0, v63, 1.0
	v_mul_f32_e32 v75, v74, v73
	v_fma_f32 v76, -v72, v75, v74
	v_fmac_f32_e32 v75, v76, v73
	v_fma_f32 v72, -v72, v75, v74
	v_div_fmas_f32 v72, v72, v73, v75
	v_div_fixup_f32 v63, v72, v63, 1.0
	v_mul_f32_e32 v72, v63, v0
	v_mul_f32_e32 v62, v72, v62
	v_mul_f32_e32 v72, v63, v14
	v_mul_f32_e32 v61, v72, v61
	v_mul_f32_e32 v72, v63, v15
	v_mul_f32_e32 v63, v63, v16
	v_mul_f32_e32 v60, v72, v60
	v_mul_f32_e32 v59, v63, v59
	flat_load_dword v63, v[8:9] offset:1792
	flat_load_dword v72, v[6:7] offset:1792
	flat_load_dword v73, v[4:5] offset:1792
	flat_load_dword v74, v[2:3] offset:1792
	s_waitcnt vmcnt(0) lgkmcnt(0)
	v_fma_f32 v63, -v17, v71, v63
	v_fma_f32 v76, -v17, v84, v72
	v_fma_f32 v75, -v17, v86, v73
	v_fma_f32 v74, -v17, v85, v74
	v_mul_f32_e32 v73, v75, v75
	v_fmac_f32_e32 v73, v74, v74
	v_fmac_f32_e32 v73, v76, v76
	v_fmac_f32_e32 v73, v63, v63
	ds_swizzle_b32 v71, v73 offset:swizzle(SWAP,1)
	s_waitcnt lgkmcnt(0)
	v_add_f32_e32 v71, v73, v71
	ds_swizzle_b32 v72, v71 offset:swizzle(SWAP,2)
	s_waitcnt lgkmcnt(0)
	v_add_f32_e32 v71, v71, v72
	ds_swizzle_b32 v72, v71 offset:swizzle(SWAP,4)
	s_waitcnt lgkmcnt(0)
	v_add_f32_e32 v71, v71, v72
	ds_swizzle_b32 v72, v71 offset:swizzle(SWAP,8)
	s_waitcnt lgkmcnt(0)
	v_add_f32_e32 v71, v71, v72
	ds_swizzle_b32 v72, v71 offset:swizzle(SWAP,16)
	s_waitcnt lgkmcnt(0)
; __global__ void __launch_bounds__(NTHR, 2) mega_fwd(Args a) {
;     ...
;               for (int r = 0; r < 16; ++r) { float ss = 0.f;
; #pragma unroll
;                   for (int d0 = 0; d0 < 4; ++d0) { const float dv = scrq[(d0 * 16 + r) * 64] - lam * o[d0][r]; o[d0][r] = dv; ss += dv * dv; }
;                   ss = half_sum(ss);
;                   const float rstd = 1.0f / sqrtf(ss * (1.f / 128.f) + EPS);
; #pragma unroll
;                   for (int d0 = 0; d0 < 4; ++d0) o[d0][r] *= rstd * gv[d0];
;                   if ((r & 3) == 3) asm volatile("" ::: "memory"); }
	v_add_f32_e32 v71, v71, v72
	v_fmamk_f32 v71, v71, 0x3c000000, v218
	v_cmp_gt_f32_e32 vcc, s68, v71
	v_mul_f32_e32 v72, 0x4f800000, v71
	s_nop 0
	v_cndmask_b32_e32 v71, v71, v72, vcc
	v_sqrt_f32_e32 v72, v71
	s_nop 0
	v_add_u32_e32 v73, -1, v72
	v_fma_f32 v77, -v73, v72, v71
	v_cmp_ge_f32_e64 s[0:1], 0, v77
	v_add_u32_e32 v77, 1, v72
	s_nop 0
	v_cndmask_b32_e64 v73, v72, v73, s[0:1]
	v_fma_f32 v72, -v77, v72, v71
	v_cmp_lt_f32_e64 s[0:1], 0, v72
	s_nop 1
	v_cndmask_b32_e64 v72, v73, v77, s[0:1]
	v_mul_f32_e32 v73, 0x37800000, v72
	v_cndmask_b32_e32 v72, v72, v73, vcc
	v_cmp_class_f32_e32 vcc, v71, v219
	s_nop 1
	v_cndmask_b32_e32 v71, v72, v71, vcc
	v_div_scale_f32 v72, s[0:1], v71, v71, 1.0
	v_rcp_f32_e32 v73, v72
	s_nop 0
	v_fma_f32 v77, -v72, v73, 1.0
	v_fmac_f32_e32 v73, v77, v73
	v_div_scale_f32 v77, vcc, 1.0, v71, 1.0
	v_mul_f32_e32 v78, v77, v73
	v_fma_f32 v79, -v72, v78, v77
	v_fmac_f32_e32 v78, v79, v73
	v_fma_f32 v72, -v72, v78, v77
	v_div_fmas_f32 v72, v72, v73, v78
	v_div_fixup_f32 v77, v72, v71, 1.0
	v_mul_f32_e32 v71, v77, v0
	v_mul_f32_e32 v73, v71, v74
	v_mul_f32_e32 v71, v77, v14
	v_mul_f32_e32 v74, v77, v16
	v_mul_f32_e32 v72, v71, v75
	v_mul_f32_e32 v71, v77, v15
	v_mul_f32_e32 v63, v74, v63
	flat_load_dword v74, v[2:3] offset:2048
	flat_load_dword v75, v[4:5] offset:2048
	flat_load_dword v77, v[6:7] offset:2048
	v_mul_f32_e32 v71, v71, v76
	s_waitcnt vmcnt(0) lgkmcnt(0)
	v_fma_f32 v74, -v17, v83, v74
	v_fma_f32 v75, -v17, v82, v75
	v_fma_f32 v78, -v17, v81, v77
	flat_load_dword v77, v[8:9] offset:2048
	v_mul_f32_e32 v76, v75, v75
	v_fmac_f32_e32 v76, v74, v74
	v_fmac_f32_e32 v76, v78, v78
	s_waitcnt vmcnt(0) lgkmcnt(0)
	v_fma_f32 v79, -v17, v80, v77
	v_fmac_f32_e32 v76, v79, v79
	ds_swizzle_b32 v77, v76 offset:swizzle(SWAP,1)
	s_waitcnt lgkmcnt(0)
	v_add_f32_e32 v76, v76, v77
	ds_swizzle_b32 v77, v76 offset:swizzle(SWAP,2)
	s_waitcnt lgkmcnt(0)
	v_add_f32_e32 v76, v76, v77
	ds_swizzle_b32 v77, v76 offset:swizzle(SWAP,4)
	s_waitcnt lgkmcnt(0)
	v_add_f32_e32 v76, v76, v77
	ds_swizzle_b32 v77, v76 offset:swizzle(SWAP,8)
	s_waitcnt lgkmcnt(0)
	v_add_f32_e32 v76, v76, v77
	ds_swizzle_b32 v77, v76 offset:swizzle(SWAP,16)
	s_waitcnt lgkmcnt(0)
	v_add_f32_e32 v76, v76, v77
	v_fmamk_f32 v76, v76, 0x3c000000, v218
	v_cmp_gt_f32_e32 vcc, s68, v76
	v_mul_f32_e32 v77, 0x4f800000, v76
	s_nop 0
	v_cndmask_b32_e32 v76, v76, v77, vcc
	v_sqrt_f32_e32 v77, v76
	s_nop 0
	v_add_u32_e32 v80, -1, v77
	v_fma_f32 v81, -v80, v77, v76
	v_cmp_ge_f32_e64 s[0:1], 0, v81
	v_add_u32_e32 v81, 1, v77
	s_nop 0
	v_cndmask_b32_e64 v80, v77, v80, s[0:1]
	v_fma_f32 v77, -v81, v77, v76
	v_cmp_lt_f32_e64 s[0:1], 0, v77
	s_nop 1
	v_cndmask_b32_e64 v77, v80, v81, s[0:1]
	v_mul_f32_e32 v80, 0x37800000, v77
	v_cndmask_b32_e32 v77, v77, v80, vcc
	v_cmp_class_f32_e32 vcc, v76, v219
	s_nop 1
	v_cndmask_b32_e32 v76, v77, v76, vcc
	v_div_scale_f32 v77, s[0:1], v76, v76, 1.0
	v_rcp_f32_e32 v80, v77
	s_nop 0
	v_fma_f32 v81, -v77, v80, 1.0
	v_fmac_f32_e32 v80, v81, v80
	v_div_scale_f32 v81, vcc, 1.0, v76, 1.0
	v_mul_f32_e32 v82, v81, v80
	v_fma_f32 v83, -v77, v82, v81
	v_fmac_f32_e32 v82, v83, v80
	v_fma_f32 v77, -v77, v82, v81
	v_div_fmas_f32 v77, v77, v80, v82
	v_div_fixup_f32 v80, v77, v76, 1.0
	v_mul_f32_e32 v76, v80, v0
	v_mul_f32_e32 v77, v76, v74
	v_mul_f32_e32 v74, v80, v14
	v_mul_f32_e32 v76, v74, v75
	v_mul_f32_e32 v74, v80, v15
	v_mul_f32_e32 v75, v74, v78
	v_mul_f32_e32 v74, v80, v16
	v_mul_f32_e32 v74, v74, v79
	flat_load_dword v78, v[8:9] offset:2304
	flat_load_dword v79, v[6:7] offset:2304
	flat_load_dword v80, v[4:5] offset:2304
	flat_load_dword v81, v[2:3] offset:2304
	s_waitcnt vmcnt(0) lgkmcnt(0)
	v_fma_f32 v67, -v17, v67, v78
	v_fma_f32 v68, -v17, v68, v79
	v_fma_f32 v80, -v17, v70, v80
	v_fma_f32 v69, -v17, v69, v81
	v_mul_f32_e32 v70, v80, v80
	v_fmac_f32_e32 v70, v69, v69
	v_fmac_f32_e32 v70, v68, v68
	v_fmac_f32_e32 v70, v67, v67
	ds_swizzle_b32 v78, v70 offset:swizzle(SWAP,1)
	s_waitcnt lgkmcnt(0)
	v_add_f32_e32 v70, v70, v78
	ds_swizzle_b32 v78, v70 offset:swizzle(SWAP,2)
	s_waitcnt lgkmcnt(0)
	v_add_f32_e32 v70, v70, v78
	ds_swizzle_b32 v78, v70 offset:swizzle(SWAP,4)
	s_waitcnt lgkmcnt(0)
	v_add_f32_e32 v70, v70, v78
	ds_swizzle_b32 v78, v70 offset:swizzle(SWAP,8)
	s_waitcnt lgkmcnt(0)
	v_add_f32_e32 v70, v70, v78
	ds_swizzle_b32 v78, v70 offset:swizzle(SWAP,16)
	s_waitcnt lgkmcnt(0)
	v_add_f32_e32 v70, v70, v78
	v_fmamk_f32 v70, v70, 0x3c000000, v218
	v_cmp_gt_f32_e32 vcc, s68, v70
	v_mul_f32_e32 v78, 0x4f800000, v70
	s_nop 0
	v_cndmask_b32_e32 v70, v70, v78, vcc
	v_sqrt_f32_e32 v78, v70
	s_nop 0
	v_add_u32_e32 v79, -1, v78
	v_fma_f32 v81, -v79, v78, v70
	v_cmp_ge_f32_e64 s[0:1], 0, v81
	v_add_u32_e32 v81, 1, v78
	s_nop 0
	v_cndmask_b32_e64 v79, v78, v79, s[0:1]
	v_fma_f32 v78, -v81, v78, v70
	v_cmp_lt_f32_e64 s[0:1], 0, v78
	s_nop 1
	v_cndmask_b32_e64 v78, v79, v81, s[0:1]
	v_mul_f32_e32 v79, 0x37800000, v78
	v_cndmask_b32_e32 v78, v78, v79, vcc
	v_cmp_class_f32_e32 vcc, v70, v219
	s_nop 1
	v_cndmask_b32_e32 v70, v78, v70, vcc
	v_div_scale_f32 v78, s[0:1], v70, v70, 1.0
	v_rcp_f32_e32 v79, v78
	s_nop 0
	v_fma_f32 v81, -v78, v79, 1.0
	v_fmac_f32_e32 v79, v81, v79
	v_div_scale_f32 v81, vcc, 1.0, v70, 1.0
	v_mul_f32_e32 v82, v81, v79
	v_fma_f32 v83, -v78, v82, v81
	v_fmac_f32_e32 v82, v83, v79
	v_fma_f32 v78, -v78, v82, v81
	v_div_fmas_f32 v78, v78, v79, v82
	v_div_fixup_f32 v78, v78, v70, 1.0
	v_mul_f32_e32 v70, v78, v0
	v_mul_f32_e32 v70, v70, v69
	v_mul_f32_e32 v69, v78, v14
	v_mul_f32_e32 v79, v78, v15
	v_mul_f32_e32 v78, v78, v16
	v_mul_f32_e32 v69, v69, v80
	v_mul_f32_e32 v68, v79, v68
	v_mul_f32_e32 v67, v78, v67
	flat_load_dword v78, v[8:9] offset:2560
	flat_load_dword v79, v[6:7] offset:2560
	flat_load_dword v80, v[4:5] offset:2560
	flat_load_dword v81, v[2:3] offset:2560
	s_waitcnt vmcnt(0) lgkmcnt(0)
; __global__ void __launch_bounds__(NTHR, 2) mega_fwd(Args a) {
;     ...
;               for (int r = 0; r < 16; ++r) { float ss = 0.f;
; #pragma unroll
;                   for (int d0 = 0; d0 < 4; ++d0) { const float dv = scrq[(d0 * 16 + r) * 64] - lam * o[d0][r]; o[d0][r] = dv; ss += dv * dv; }
;                   ss = half_sum(ss);
;                   const float rstd = 1.0f / sqrtf(ss * (1.f / 128.f) + EPS);
; #pragma unroll
;                   for (int d0 = 0; d0 < 4; ++d0) o[d0][r] *= rstd * gv[d0];
;                   if ((r & 3) == 3) asm volatile("" ::: "memory"); }
	v_fma_f32 v58, -v17, v58, v78
	v_fma_f32 v64, -v17, v64, v79
	v_fma_f32 v80, -v17, v66, v80
	v_fma_f32 v65, -v17, v65, v81
	v_mul_f32_e32 v66, v80, v80
	v_fmac_f32_e32 v66, v65, v65
	v_fmac_f32_e32 v66, v64, v64
	v_fmac_f32_e32 v66, v58, v58
	ds_swizzle_b32 v78, v66 offset:swizzle(SWAP,1)
	s_waitcnt lgkmcnt(0)
	v_add_f32_e32 v66, v66, v78
	ds_swizzle_b32 v78, v66 offset:swizzle(SWAP,2)
	s_waitcnt lgkmcnt(0)
	v_add_f32_e32 v66, v66, v78
	ds_swizzle_b32 v78, v66 offset:swizzle(SWAP,4)
	s_waitcnt lgkmcnt(0)
	v_add_f32_e32 v66, v66, v78
	ds_swizzle_b32 v78, v66 offset:swizzle(SWAP,8)
	s_waitcnt lgkmcnt(0)
	v_add_f32_e32 v66, v66, v78
	ds_swizzle_b32 v78, v66 offset:swizzle(SWAP,16)
	s_waitcnt lgkmcnt(0)
	v_add_f32_e32 v66, v66, v78
	v_fmamk_f32 v66, v66, 0x3c000000, v218
	v_cmp_gt_f32_e32 vcc, s68, v66
	v_mul_f32_e32 v78, 0x4f800000, v66
	s_nop 0
	v_cndmask_b32_e32 v66, v66, v78, vcc
	v_sqrt_f32_e32 v78, v66
	s_nop 0
	v_add_u32_e32 v79, -1, v78
	v_fma_f32 v81, -v79, v78, v66
	v_cmp_ge_f32_e64 s[0:1], 0, v81
	v_add_u32_e32 v81, 1, v78
	s_nop 0
	v_cndmask_b32_e64 v79, v78, v79, s[0:1]
	v_fma_f32 v78, -v81, v78, v66
	v_cmp_lt_f32_e64 s[0:1], 0, v78
	s_nop 1
	v_cndmask_b32_e64 v78, v79, v81, s[0:1]
	v_mul_f32_e32 v79, 0x37800000, v78
	v_cndmask_b32_e32 v78, v78, v79, vcc
	v_cmp_class_f32_e32 vcc, v66, v219
	s_nop 1
	v_cndmask_b32_e32 v66, v78, v66, vcc
	v_div_scale_f32 v78, s[0:1], v66, v66, 1.0
	v_rcp_f32_e32 v79, v78
	s_nop 0
	v_fma_f32 v81, -v78, v79, 1.0
	v_fmac_f32_e32 v79, v81, v79
	v_div_scale_f32 v81, vcc, 1.0, v66, 1.0
	v_mul_f32_e32 v82, v81, v79
	v_fma_f32 v83, -v78, v82, v81
	v_fmac_f32_e32 v82, v83, v79
	v_fma_f32 v78, -v78, v82, v81
	v_div_fmas_f32 v78, v78, v79, v82
	v_div_fixup_f32 v78, v78, v66, 1.0
	v_mul_f32_e32 v66, v78, v0
	v_mul_f32_e32 v66, v66, v65
	v_mul_f32_e32 v65, v78, v14
	v_mul_f32_e32 v79, v78, v15
	v_mul_f32_e32 v78, v78, v16
	v_mul_f32_e32 v65, v65, v80
	v_mul_f32_e32 v64, v79, v64
	v_mul_f32_e32 v58, v78, v58
	flat_load_dword v78, v[8:9] offset:2816
	flat_load_dword v79, v[6:7] offset:2816
	flat_load_dword v80, v[4:5] offset:2816
	flat_load_dword v81, v[2:3] offset:2816
	s_waitcnt vmcnt(0) lgkmcnt(0)
	v_fma_f32 v50, -v17, v50, v78
	v_fma_f32 v51, -v17, v51, v79
	v_fma_f32 v80, -v17, v53, v80
	v_fma_f32 v52, -v17, v52, v81
	v_mul_f32_e32 v53, v80, v80
	v_fmac_f32_e32 v53, v52, v52
	v_fmac_f32_e32 v53, v51, v51
	v_fmac_f32_e32 v53, v50, v50
	ds_swizzle_b32 v78, v53 offset:swizzle(SWAP,1)
	s_waitcnt lgkmcnt(0)
	v_add_f32_e32 v53, v53, v78
	ds_swizzle_b32 v78, v53 offset:swizzle(SWAP,2)
	s_waitcnt lgkmcnt(0)
	v_add_f32_e32 v53, v53, v78
	ds_swizzle_b32 v78, v53 offset:swizzle(SWAP,4)
	s_waitcnt lgkmcnt(0)
	v_add_f32_e32 v53, v53, v78
	ds_swizzle_b32 v78, v53 offset:swizzle(SWAP,8)
	s_waitcnt lgkmcnt(0)
	v_add_f32_e32 v53, v53, v78
	ds_swizzle_b32 v78, v53 offset:swizzle(SWAP,16)
	s_waitcnt lgkmcnt(0)
	v_add_f32_e32 v53, v53, v78
	v_fmamk_f32 v53, v53, 0x3c000000, v218
	v_cmp_gt_f32_e32 vcc, s68, v53
	v_mul_f32_e32 v78, 0x4f800000, v53
	s_nop 0
	v_cndmask_b32_e32 v53, v53, v78, vcc
	v_sqrt_f32_e32 v78, v53
	s_nop 0
	v_add_u32_e32 v79, -1, v78
	v_fma_f32 v81, -v79, v78, v53
	v_cmp_ge_f32_e64 s[0:1], 0, v81
	v_add_u32_e32 v81, 1, v78
	s_nop 0
	v_cndmask_b32_e64 v79, v78, v79, s[0:1]
	v_fma_f32 v78, -v81, v78, v53
	v_cmp_lt_f32_e64 s[0:1], 0, v78
	s_nop 1
	v_cndmask_b32_e64 v78, v79, v81, s[0:1]
	v_mul_f32_e32 v79, 0x37800000, v78
	v_cndmask_b32_e32 v78, v78, v79, vcc
	v_cmp_class_f32_e32 vcc, v53, v219
	s_nop 1
	v_cndmask_b32_e32 v53, v78, v53, vcc
	v_div_scale_f32 v78, s[0:1], v53, v53, 1.0
	v_rcp_f32_e32 v79, v78
	s_nop 0
	v_fma_f32 v81, -v78, v79, 1.0
	v_fmac_f32_e32 v79, v81, v79
	v_div_scale_f32 v81, vcc, 1.0, v53, 1.0
	v_mul_f32_e32 v82, v81, v79
	v_fma_f32 v83, -v78, v82, v81
	v_fmac_f32_e32 v82, v83, v79
	v_fma_f32 v78, -v78, v82, v81
	v_div_fmas_f32 v78, v78, v79, v82
	v_div_fixup_f32 v78, v78, v53, 1.0
	v_mul_f32_e32 v53, v78, v0
	v_mul_f32_e32 v53, v53, v52
	v_mul_f32_e32 v52, v78, v14
	v_mul_f32_e32 v79, v78, v15
	v_mul_f32_e32 v78, v78, v16
	v_mul_f32_e32 v50, v78, v50
	flat_load_dword v78, v[2:3] offset:3072
	v_mul_f32_e32 v51, v79, v51
	flat_load_dword v79, v[6:7] offset:3072
	v_mul_f32_e32 v52, v52, v80
	s_waitcnt vmcnt(0) lgkmcnt(0)
	v_fma_f32 v49, -v17, v49, v78
	flat_load_dword v78, v[4:5] offset:3072
	v_fma_f32 v43, -v17, v43, v79
	flat_load_dword v79, v[8:9] offset:3072
	s_waitcnt vmcnt(0) lgkmcnt(0)
	v_fma_f32 v48, -v17, v48, v78
	v_mul_f32_e32 v78, v48, v48
	v_fmac_f32_e32 v78, v49, v49
	v_fmac_f32_e32 v78, v43, v43
	v_fma_f32 v42, -v17, v42, v79
	v_fmac_f32_e32 v78, v42, v42
	ds_swizzle_b32 v79, v78 offset:swizzle(SWAP,1)
	s_waitcnt lgkmcnt(0)
	v_add_f32_e32 v78, v78, v79
	ds_swizzle_b32 v79, v78 offset:swizzle(SWAP,2)
	s_waitcnt lgkmcnt(0)
	v_add_f32_e32 v78, v78, v79
	ds_swizzle_b32 v79, v78 offset:swizzle(SWAP,4)
	s_waitcnt lgkmcnt(0)
	v_add_f32_e32 v78, v78, v79
	ds_swizzle_b32 v79, v78 offset:swizzle(SWAP,8)
	s_waitcnt lgkmcnt(0)
	v_add_f32_e32 v78, v78, v79
	ds_swizzle_b32 v79, v78 offset:swizzle(SWAP,16)
	s_waitcnt lgkmcnt(0)
; __global__ void __launch_bounds__(NTHR, 2) mega_fwd(Args a) {
;     ...
;               for (int r = 0; r < 16; ++r) { float ss = 0.f;
; #pragma unroll
;                   for (int d0 = 0; d0 < 4; ++d0) { const float dv = scrq[(d0 * 16 + r) * 64] - lam * o[d0][r]; o[d0][r] = dv; ss += dv * dv; }
;                   ss = half_sum(ss);
;                   const float rstd = 1.0f / sqrtf(ss * (1.f / 128.f) + EPS);
; #pragma unroll
;                   for (int d0 = 0; d0 < 4; ++d0) o[d0][r] *= rstd * gv[d0];
;                   if ((r & 3) == 3) asm volatile("" ::: "memory"); }
	v_add_f32_e32 v78, v78, v79
	v_fmamk_f32 v78, v78, 0x3c000000, v218
	v_cmp_gt_f32_e32 vcc, s68, v78
	v_mul_f32_e32 v79, 0x4f800000, v78
	s_nop 0
	v_cndmask_b32_e32 v78, v78, v79, vcc
	v_sqrt_f32_e32 v79, v78
	s_nop 0
	v_add_u32_e32 v80, -1, v79
	v_fma_f32 v81, -v80, v79, v78
	v_cmp_ge_f32_e64 s[0:1], 0, v81
	v_add_u32_e32 v81, 1, v79
	s_nop 0
	v_cndmask_b32_e64 v80, v79, v80, s[0:1]
	v_fma_f32 v79, -v81, v79, v78
	v_cmp_lt_f32_e64 s[0:1], 0, v79
	s_nop 1
	v_cndmask_b32_e64 v79, v80, v81, s[0:1]
	v_mul_f32_e32 v80, 0x37800000, v79
	v_cndmask_b32_e32 v79, v79, v80, vcc
	v_cmp_class_f32_e32 vcc, v78, v219
	s_nop 1
	v_cndmask_b32_e32 v78, v79, v78, vcc
	v_div_scale_f32 v79, s[0:1], v78, v78, 1.0
	v_rcp_f32_e32 v80, v79
	s_nop 0
	v_fma_f32 v81, -v79, v80, 1.0
	v_fmac_f32_e32 v80, v81, v80
	v_div_scale_f32 v81, vcc, 1.0, v78, 1.0
	v_mul_f32_e32 v82, v81, v80
	v_fma_f32 v83, -v79, v82, v81
	v_fmac_f32_e32 v82, v83, v80
	v_fma_f32 v79, -v79, v82, v81
	v_div_fmas_f32 v79, v79, v80, v82
	v_div_fixup_f32 v78, v79, v78, 1.0
	v_mul_f32_e32 v79, v78, v0
	v_mul_f32_e32 v49, v79, v49
	v_mul_f32_e32 v79, v78, v14
	v_mul_f32_e32 v48, v79, v48
	v_mul_f32_e32 v79, v78, v15
	v_mul_f32_e32 v78, v78, v16
	v_mul_f32_e32 v43, v79, v43
	v_mul_f32_e32 v42, v78, v42
	flat_load_dword v78, v[8:9] offset:3328
	flat_load_dword v79, v[6:7] offset:3328
	flat_load_dword v80, v[4:5] offset:3328
	flat_load_dword v81, v[2:3] offset:3328
	s_waitcnt vmcnt(0) lgkmcnt(0)
	v_fma_f32 v34, -v17, v34, v78
	v_fma_f32 v35, -v17, v35, v79
	v_fma_f32 v80, -v17, v37, v80
	v_fma_f32 v36, -v17, v36, v81
	v_mul_f32_e32 v37, v80, v80
	v_fmac_f32_e32 v37, v36, v36
	v_fmac_f32_e32 v37, v35, v35
	v_fmac_f32_e32 v37, v34, v34
	ds_swizzle_b32 v78, v37 offset:swizzle(SWAP,1)
	s_waitcnt lgkmcnt(0)
	v_add_f32_e32 v37, v37, v78
	ds_swizzle_b32 v78, v37 offset:swizzle(SWAP,2)
	s_waitcnt lgkmcnt(0)
	v_add_f32_e32 v37, v37, v78
	ds_swizzle_b32 v78, v37 offset:swizzle(SWAP,4)
	s_waitcnt lgkmcnt(0)
	v_add_f32_e32 v37, v37, v78
	ds_swizzle_b32 v78, v37 offset:swizzle(SWAP,8)
	s_waitcnt lgkmcnt(0)
	v_add_f32_e32 v37, v37, v78
	ds_swizzle_b32 v78, v37 offset:swizzle(SWAP,16)
	s_waitcnt lgkmcnt(0)
	v_add_f32_e32 v37, v37, v78
	v_fmamk_f32 v37, v37, 0x3c000000, v218
	v_cmp_gt_f32_e32 vcc, s68, v37
	v_mul_f32_e32 v78, 0x4f800000, v37
	s_nop 0
	v_cndmask_b32_e32 v37, v37, v78, vcc
	v_sqrt_f32_e32 v78, v37
	s_nop 0
	v_add_u32_e32 v79, -1, v78
	v_fma_f32 v81, -v79, v78, v37
	v_cmp_ge_f32_e64 s[0:1], 0, v81
	v_add_u32_e32 v81, 1, v78
	s_nop 0
	v_cndmask_b32_e64 v79, v78, v79, s[0:1]
	v_fma_f32 v78, -v81, v78, v37
	v_cmp_lt_f32_e64 s[0:1], 0, v78
	s_nop 1
	v_cndmask_b32_e64 v78, v79, v81, s[0:1]
	v_mul_f32_e32 v79, 0x37800000, v78
	v_cndmask_b32_e32 v78, v78, v79, vcc
	v_cmp_class_f32_e32 vcc, v37, v219
	s_nop 1
	v_cndmask_b32_e32 v37, v78, v37, vcc
	v_div_scale_f32 v78, s[0:1], v37, v37, 1.0
	v_rcp_f32_e32 v79, v78
	s_nop 0
	v_fma_f32 v81, -v78, v79, 1.0
	v_fmac_f32_e32 v79, v81, v79
	v_div_scale_f32 v81, vcc, 1.0, v37, 1.0
	v_mul_f32_e32 v82, v81, v79
	v_fma_f32 v83, -v78, v82, v81
	v_fmac_f32_e32 v82, v83, v79
	v_fma_f32 v78, -v78, v82, v81
	v_div_fmas_f32 v78, v78, v79, v82
	v_div_fixup_f32 v78, v78, v37, 1.0
	v_mul_f32_e32 v37, v78, v0
	v_mul_f32_e32 v37, v37, v36
	v_mul_f32_e32 v36, v78, v14
	v_mul_f32_e32 v79, v78, v15
	v_mul_f32_e32 v78, v78, v16
	v_mul_f32_e32 v36, v36, v80
	v_mul_f32_e32 v35, v79, v35
	v_mul_f32_e32 v34, v78, v34
	flat_load_dword v78, v[8:9] offset:3584
	flat_load_dword v79, v[6:7] offset:3584
	flat_load_dword v80, v[4:5] offset:3584
	flat_load_dword v81, v[2:3] offset:3584
	s_nop 0
	flat_load_dword v8, v[8:9] offset:3840
	s_nop 0
	flat_load_dword v6, v[6:7] offset:3840
	s_nop 0
	flat_load_dword v4, v[4:5] offset:3840
	s_nop 0
	flat_load_dword v2, v[2:3] offset:3840
	s_waitcnt vmcnt(0) lgkmcnt(0)
	v_fma_f32 v26, -v17, v26, v78
	v_fma_f32 v27, -v17, v27, v79
	v_fma_f32 v80, -v17, v29, v80
	v_fma_f32 v28, -v17, v28, v81
	v_mul_f32_e32 v29, v80, v80
	v_fmac_f32_e32 v29, v28, v28
	v_fmac_f32_e32 v29, v27, v27
	v_fmac_f32_e32 v29, v26, v26
	ds_swizzle_b32 v78, v29 offset:swizzle(SWAP,1)
	v_fma_f32 v3, -v17, v13, v4
	v_fma_f32 v2, -v17, v12, v2
	v_mul_f32_e32 v4, v3, v3
	v_fmac_f32_e32 v4, v2, v2
	s_waitcnt lgkmcnt(0)
	v_add_f32_e32 v29, v29, v78
	ds_swizzle_b32 v78, v29 offset:swizzle(SWAP,2)
	v_fma_f32 v5, -v17, v11, v6
	v_fmac_f32_e32 v4, v5, v5
	v_fma_f32 v6, -v17, v10, v8
	v_fmac_f32_e32 v4, v6, v6
	s_waitcnt lgkmcnt(0)
	v_add_f32_e32 v29, v29, v78
	ds_swizzle_b32 v78, v29 offset:swizzle(SWAP,4)
	ds_swizzle_b32 v7, v4 offset:swizzle(SWAP,1)
	s_waitcnt lgkmcnt(1)
	v_add_f32_e32 v29, v29, v78
	ds_swizzle_b32 v78, v29 offset:swizzle(SWAP,8)
	s_waitcnt lgkmcnt(1)
	v_add_f32_e32 v4, v4, v7
	ds_swizzle_b32 v7, v4 offset:swizzle(SWAP,2)
	s_waitcnt lgkmcnt(1)
	v_add_f32_e32 v29, v29, v78
	ds_swizzle_b32 v78, v29 offset:swizzle(SWAP,16)
	s_waitcnt lgkmcnt(1)
	v_add_f32_e32 v4, v4, v7
	ds_swizzle_b32 v7, v4 offset:swizzle(SWAP,4)
	s_waitcnt lgkmcnt(1)
	v_add_f32_e32 v29, v29, v78
	v_fmamk_f32 v29, v29, 0x3c000000, v218
	v_cmp_gt_f32_e32 vcc, s68, v29
	v_mul_f32_e32 v78, 0x4f800000, v29
	s_waitcnt lgkmcnt(0)
	v_add_f32_e32 v4, v4, v7
	v_cndmask_b32_e32 v29, v29, v78, vcc
	v_sqrt_f32_e32 v78, v29
	ds_swizzle_b32 v7, v4 offset:swizzle(SWAP,8)
	v_add_u32_e32 v79, -1, v78
	v_fma_f32 v81, -v79, v78, v29
	v_cmp_ge_f32_e64 s[0:1], 0, v81
	v_add_u32_e32 v81, 1, v78
	s_waitcnt lgkmcnt(0)
	v_add_f32_e32 v4, v4, v7
	v_cndmask_b32_e64 v79, v78, v79, s[0:1]
	v_fma_f32 v78, -v81, v78, v29
	v_cmp_lt_f32_e64 s[0:1], 0, v78
	ds_swizzle_b32 v7, v4 offset:swizzle(SWAP,16)
	s_waitcnt lgkmcnt(0)
; __device__ __forceinline__ int tid_of(int wave_s) { int l; asm volatile("v_mbcnt_lo_u32_b32 %0, -1, 0\n\tv_mbcnt_hi_u32_b32 %0, -1, %0" : "=v"(l)); return wave_s * 64 + l; }
; __device__ __forceinline__ unsigned f2bf(float f) { unsigned u = __builtin_bit_cast(unsigned, f); return (u + 0x7fffu + ((u >> 16) & 1u)) >> 16; }
; __device__ __forceinline__ int crow(int r, int hi) { return (r & 3) + 8 * (r >> 2) + 4 * hi; }
; __device__ __forceinline__ void store_o_tile(const f32x16 (&o)[4], char* lds, bf16_t* Og, int wave_s) {
;     int tid_ = tid_of(wave_s);
;     const int wid = tid_ >> 6, lane = tid_ & 63, r32 = lane & 31, hi = lane >> 5;
;     __syncthreads();
;     bf16_t* stg = (bf16_t*)(lds + wid * 8192);
; #pragma unroll
;     for (int r = 0; r < 16; ++r) { const int orow = att::crow(r, hi);
; #pragma unroll
;         for (int d0 = 0; d0 < 4; ++d0) stg[orow * 128 + d0 * 32 + r32] = (bf16_t)f2bf(o[d0][r]); }
; __global__ void __launch_bounds__(NTHR, 2) mega_fwd(Args a) {
;     ...
;               for (int r = 0; r < 16; ++r) { float ss = 0.f;
; #pragma unroll
;                   for (int d0 = 0; d0 < 4; ++d0) { const float dv = scrq[(d0 * 16 + r) * 64] - lam * o[d0][r]; o[d0][r] = dv; ss += dv * dv; }
;                   ss = half_sum(ss);
;                   const float rstd = 1.0f / sqrtf(ss * (1.f / 128.f) + EPS);
; #pragma unroll
;                   for (int d0 = 0; d0 < 4; ++d0) o[d0][r] *= rstd * gv[d0];
;                   if ((r & 3) == 3) asm volatile("" ::: "memory"); }
;               store_o_tile(o, (char*)lds, O + (size_t)(q0 + wid * 32) * DM + (12 + hd) * 128, wave_s); }
	v_add_f32_e32 v4, v4, v7
	v_cndmask_b32_e64 v78, v79, v81, s[0:1]
	v_mul_f32_e32 v79, 0x37800000, v78
	v_cndmask_b32_e32 v78, v78, v79, vcc
	v_cmp_class_f32_e32 vcc, v29, v219
	v_fmamk_f32 v4, v4, 0x3c000000, v218
	v_mul_f32_e32 v7, 0x4f800000, v4
	v_cndmask_b32_e32 v29, v78, v29, vcc
	v_div_scale_f32 v78, s[0:1], v29, v29, 1.0
	v_rcp_f32_e32 v79, v78
	s_nop 0
	v_fma_f32 v81, -v78, v79, 1.0
	v_fmac_f32_e32 v79, v81, v79
	v_div_scale_f32 v81, vcc, 1.0, v29, 1.0
	v_mul_f32_e32 v82, v81, v79
	v_fma_f32 v83, -v78, v82, v81
	v_fmac_f32_e32 v82, v83, v79
	v_fma_f32 v78, -v78, v82, v81
	v_div_fmas_f32 v78, v78, v79, v82
	v_cmp_gt_f32_e32 vcc, s68, v4
	v_div_fixup_f32 v78, v78, v29, 1.0
	v_mul_f32_e32 v29, v78, v0
	v_cndmask_b32_e32 v4, v4, v7, vcc
	v_sqrt_f32_e32 v7, v4
	v_mul_f32_e32 v29, v29, v28
	v_mul_f32_e32 v28, v78, v14
	v_mul_f32_e32 v28, v28, v80
	v_add_u32_e32 v8, -1, v7
	v_fma_f32 v9, -v8, v7, v4
	v_cmp_ge_f32_e64 s[0:1], 0, v9
	v_add_u32_e32 v9, 1, v7
	v_mul_f32_e32 v79, v78, v15
	v_cndmask_b32_e64 v8, v7, v8, s[0:1]
	v_fma_f32 v7, -v9, v7, v4
	v_cmp_lt_f32_e64 s[0:1], 0, v7
	v_mul_f32_e32 v27, v79, v27
	v_mul_f32_e32 v78, v78, v16
	v_cndmask_b32_e64 v7, v8, v9, s[0:1]
	v_mul_f32_e32 v8, 0x37800000, v7
	v_cndmask_b32_e32 v7, v7, v8, vcc
	v_cmp_class_f32_e32 vcc, v4, v219
	v_mul_f32_e32 v26, v78, v26
	s_nop 0
	v_cndmask_b32_e32 v4, v7, v4, vcc
	v_div_scale_f32 v7, s[0:1], v4, v4, 1.0
	v_rcp_f32_e32 v8, v7
	v_readlane_b32 s0, v254, 11
	v_fma_f32 v9, -v7, v8, 1.0
	v_fmac_f32_e32 v8, v9, v8
	v_div_scale_f32 v9, vcc, 1.0, v4, 1.0
	v_mul_f32_e32 v10, v9, v8
	v_fma_f32 v11, -v7, v10, v9
	v_fmac_f32_e32 v10, v11, v8
	v_fma_f32 v7, -v7, v10, v9
	v_div_fmas_f32 v7, v7, v8, v10
	v_div_fixup_f32 v4, v7, v4, 1.0
	v_mul_f32_e32 v0, v4, v0
	v_mul_f32_e32 v0, v0, v2
	v_mul_f32_e32 v2, v4, v14
	v_mul_f32_e32 v7, v2, v3
	v_mul_f32_e32 v2, v4, v15
	v_mul_f32_e32 v5, v2, v5
	v_mul_f32_e32 v2, v4, v16
	v_mul_f32_e32 v4, v2, v6
	v_mbcnt_lo_u32_b32 v6, -1, 0
	v_mbcnt_hi_u32_b32 v6, -1, v6
	s_nop 0
	v_lshl_add_u32 v9, v6, 7, s0
	v_and_b32_e32 v8, 31, v6
	v_and_b32_e32 v9, 0xffffe000, v9
	v_lshlrev_b32_e32 v10, 5, v6
	v_add_u32_e32 v9, 0, v9
	v_lshlrev_b32_e32 v8, 1, v8
	v_and_b32_e32 v10, 0x400, v10
	v_add3_u32 v8, v9, v8, v10
	v_bfe_u32 v10, v21, 16, 1
	v_add3_u32 v10, v21, v10, s33
	s_barrier
	ds_write_b16_d16_hi v8, v10
	v_bfe_u32 v10, v20, 16, 1
	v_add3_u32 v10, v20, v10, s33
	ds_write_b16_d16_hi v8, v10 offset:64
	v_bfe_u32 v10, v19, 16, 1
	v_add3_u32 v10, v19, v10, s33
	ds_write_b16_d16_hi v8, v10 offset:128
	v_bfe_u32 v10, v18, 16, 1
	v_add3_u32 v10, v18, v10, s33
	ds_write_b16_d16_hi v8, v10 offset:192
	v_bfe_u32 v10, v25, 16, 1
	v_add3_u32 v10, v25, v10, s33
	ds_write_b16_d16_hi v8, v10 offset:256
	v_bfe_u32 v10, v24, 16, 1
	v_add3_u32 v10, v24, v10, s33
	ds_write_b16_d16_hi v8, v10 offset:320
	v_bfe_u32 v10, v23, 16, 1
	v_add3_u32 v10, v23, v10, s33
	ds_write_b16_d16_hi v8, v10 offset:384
	v_bfe_u32 v10, v22, 16, 1
	v_add3_u32 v10, v22, v10, s33
	ds_write_b16_d16_hi v8, v10 offset:448
	v_bfe_u32 v10, v33, 16, 1
	v_add3_u32 v10, v33, v10, s33
	ds_write_b16_d16_hi v8, v10 offset:512
	v_bfe_u32 v10, v32, 16, 1
	v_add3_u32 v10, v32, v10, s33
	ds_write_b16_d16_hi v8, v10 offset:576
	v_bfe_u32 v10, v31, 16, 1
	v_add3_u32 v10, v31, v10, s33
	ds_write_b16_d16_hi v8, v10 offset:640
	v_bfe_u32 v10, v30, 16, 1
	v_add3_u32 v10, v30, v10, s33
	ds_write_b16_d16_hi v8, v10 offset:704
	v_bfe_u32 v10, v41, 16, 1
	v_add3_u32 v10, v41, v10, s33
	ds_write_b16_d16_hi v8, v10 offset:768
	v_bfe_u32 v10, v40, 16, 1
	v_add3_u32 v10, v40, v10, s33
	ds_write_b16_d16_hi v8, v10 offset:832
	v_bfe_u32 v10, v39, 16, 1
	v_add3_u32 v10, v39, v10, s33
	ds_write_b16_d16_hi v8, v10 offset:896
	v_bfe_u32 v10, v38, 16, 1
	v_add3_u32 v10, v38, v10, s33
	ds_write_b16_d16_hi v8, v10 offset:960
	v_bfe_u32 v10, v47, 16, 1
	v_add3_u32 v10, v47, v10, s33
	ds_write_b16_d16_hi v8, v10 offset:2048
	v_bfe_u32 v10, v46, 16, 1
	v_add3_u32 v10, v46, v10, s33
	ds_write_b16_d16_hi v8, v10 offset:2112
	v_bfe_u32 v10, v45, 16, 1
	v_add3_u32 v10, v45, v10, s33
	ds_write_b16_d16_hi v8, v10 offset:2176
	v_bfe_u32 v10, v44, 16, 1
	v_add3_u32 v10, v44, v10, s33
	ds_write_b16_d16_hi v8, v10 offset:2240
	v_bfe_u32 v10, v57, 16, 1
	v_add3_u32 v10, v57, v10, s33
	ds_write_b16_d16_hi v8, v10 offset:2304
	v_bfe_u32 v10, v56, 16, 1
	v_add3_u32 v10, v56, v10, s33
	ds_write_b16_d16_hi v8, v10 offset:2368
	v_bfe_u32 v10, v55, 16, 1
	v_add3_u32 v10, v55, v10, s33
	ds_write_b16_d16_hi v8, v10 offset:2432
	v_bfe_u32 v10, v54, 16, 1
	v_add3_u32 v10, v54, v10, s33
	ds_write_b16_d16_hi v8, v10 offset:2496
	v_bfe_u32 v10, v62, 16, 1
	v_add3_u32 v10, v62, v10, s33
	ds_write_b16_d16_hi v8, v10 offset:2560
	v_bfe_u32 v10, v61, 16, 1
	v_add3_u32 v10, v61, v10, s33
	ds_write_b16_d16_hi v8, v10 offset:2624
	v_bfe_u32 v10, v60, 16, 1
	v_add3_u32 v10, v60, v10, s33
	ds_write_b16_d16_hi v8, v10 offset:2688
	v_bfe_u32 v10, v59, 16, 1
	v_add3_u32 v10, v59, v10, s33
	ds_write_b16_d16_hi v8, v10 offset:2752
	v_bfe_u32 v10, v73, 16, 1
	v_add3_u32 v10, v73, v10, s33
	ds_write_b16_d16_hi v8, v10 offset:2816
	v_bfe_u32 v10, v72, 16, 1
	v_add3_u32 v10, v72, v10, s33
	ds_write_b16_d16_hi v8, v10 offset:2880
	v_bfe_u32 v10, v71, 16, 1
	v_add3_u32 v10, v71, v10, s33
	ds_write_b16_d16_hi v8, v10 offset:2944
	v_bfe_u32 v10, v63, 16, 1
	v_add3_u32 v10, v63, v10, s33
	ds_write_b16_d16_hi v8, v10 offset:3008
	v_bfe_u32 v10, v77, 16, 1
	v_add3_u32 v10, v77, v10, s33
	ds_write_b16_d16_hi v8, v10 offset:4096
	v_bfe_u32 v10, v76, 16, 1
	v_add3_u32 v10, v76, v10, s33
	ds_write_b16_d16_hi v8, v10 offset:4160
	v_bfe_u32 v10, v75, 16, 1
; __device__ __forceinline__ unsigned f2bf(float f) { unsigned u = __builtin_bit_cast(unsigned, f); return (u + 0x7fffu + ((u >> 16) & 1u)) >> 16; }
; __device__ __forceinline__ int crow(int r, int hi) { return (r & 3) + 8 * (r >> 2) + 4 * hi; }
; #define PH unsigned char* ws = a.ws; asm volatile("" : "+s"(ws)); int lq = l; asm volatile("" : "+s"(lq)); (void)lq;
; __device__ __forceinline__ void store_o_tile(const f32x16 (&o)[4], char* lds, bf16_t* Og, int wave_s) {
;     ...
;     for (int r = 0; r < 16; ++r) { const int orow = att::crow(r, hi);
; #pragma unroll
;         for (int d0 = 0; d0 < 4; ++d0) stg[orow * 128 + d0 * 32 + r32] = (bf16_t)f2bf(o[d0][r]); }
;     asm volatile("s_waitcnt lgkmcnt(0)" ::: "memory");
; #pragma unroll
;     for (int i = 0; i < 8; ++i) { const int row = i * 4 + (lane >> 4), ch = lane & 15; const u32x4 v = *(const u32x4*)(stg + row * 128 + ch * 8); *(u32x4*)(Og + (size_t)row * DM + ch * 8) = v;
;         if (i & 1) asm volatile("" ::: "memory"); }
;     asm volatile("s_waitcnt lgkmcnt(0)" ::: "memory");
; __global__ void __launch_bounds__(NTHR, 2) mega_fwd(Args a) {
;     ...
;         for (int u = vcu; u < 256; u += G) { PH
	v_add3_u32 v10, v75, v10, s33
	ds_write_b16_d16_hi v8, v10 offset:4224
	v_bfe_u32 v10, v74, 16, 1
	v_add3_u32 v10, v74, v10, s33
	ds_write_b16_d16_hi v8, v10 offset:4288
	v_bfe_u32 v10, v70, 16, 1
	v_add3_u32 v10, v70, v10, s33
	ds_write_b16_d16_hi v8, v10 offset:4352
	v_bfe_u32 v10, v69, 16, 1
	v_add3_u32 v10, v69, v10, s33
	ds_write_b16_d16_hi v8, v10 offset:4416
	v_bfe_u32 v10, v68, 16, 1
	v_add3_u32 v10, v68, v10, s33
	ds_write_b16_d16_hi v8, v10 offset:4480
	v_bfe_u32 v10, v67, 16, 1
	v_add3_u32 v10, v67, v10, s33
	ds_write_b16_d16_hi v8, v10 offset:4544
	v_bfe_u32 v10, v66, 16, 1
	v_add3_u32 v10, v66, v10, s33
	ds_write_b16_d16_hi v8, v10 offset:4608
	v_bfe_u32 v10, v65, 16, 1
	v_add3_u32 v10, v65, v10, s33
	ds_write_b16_d16_hi v8, v10 offset:4672
	v_bfe_u32 v10, v64, 16, 1
	v_add3_u32 v10, v64, v10, s33
	ds_write_b16_d16_hi v8, v10 offset:4736
	v_bfe_u32 v10, v58, 16, 1
	v_add3_u32 v10, v58, v10, s33
	ds_write_b16_d16_hi v8, v10 offset:4800
	v_bfe_u32 v10, v53, 16, 1
	v_add3_u32 v10, v53, v10, s33
	ds_write_b16_d16_hi v8, v10 offset:4864
	v_bfe_u32 v10, v52, 16, 1
	v_add3_u32 v10, v52, v10, s33
	ds_write_b16_d16_hi v8, v10 offset:4928
	v_bfe_u32 v10, v51, 16, 1
	v_add3_u32 v10, v51, v10, s33
	ds_write_b16_d16_hi v8, v10 offset:4992
	v_bfe_u32 v10, v50, 16, 1
	v_add3_u32 v10, v50, v10, s33
	ds_write_b16_d16_hi v8, v10 offset:5056
	v_bfe_u32 v10, v49, 16, 1
	v_add3_u32 v10, v49, v10, s33
	ds_write_b16_d16_hi v8, v10 offset:6144
	v_bfe_u32 v10, v48, 16, 1
	v_add3_u32 v10, v48, v10, s33
	ds_write_b16_d16_hi v8, v10 offset:6208
	v_bfe_u32 v10, v43, 16, 1
	v_add3_u32 v10, v43, v10, s33
	ds_write_b16_d16_hi v8, v10 offset:6272
	v_bfe_u32 v10, v42, 16, 1
	v_add3_u32 v10, v42, v10, s33
	ds_write_b16_d16_hi v8, v10 offset:6336
	v_bfe_u32 v10, v37, 16, 1
	v_add3_u32 v10, v37, v10, s33
	ds_write_b16_d16_hi v8, v10 offset:6400
	v_bfe_u32 v10, v36, 16, 1
	v_add3_u32 v10, v36, v10, s33
	ds_write_b16_d16_hi v8, v10 offset:6464
	v_bfe_u32 v10, v35, 16, 1
	v_add3_u32 v10, v35, v10, s33
	ds_write_b16_d16_hi v8, v10 offset:6528
	v_bfe_u32 v10, v34, 16, 1
	v_add3_u32 v10, v34, v10, s33
	ds_write_b16_d16_hi v8, v10 offset:6592
	v_bfe_u32 v10, v29, 16, 1
	v_add3_u32 v10, v29, v10, s33
	ds_write_b16_d16_hi v8, v10 offset:6656
	v_bfe_u32 v10, v28, 16, 1
	v_add3_u32 v10, v28, v10, s33
	ds_write_b16_d16_hi v8, v10 offset:6720
	v_bfe_u32 v10, v27, 16, 1
	v_add3_u32 v10, v27, v10, s33
	ds_write_b16_d16_hi v8, v10 offset:6784
	v_bfe_u32 v10, v26, 16, 1
	v_add3_u32 v10, v26, v10, s33
	ds_write_b16_d16_hi v8, v10 offset:6848
	v_bfe_u32 v10, v0, 16, 1
	v_add3_u32 v0, v0, v10, s33
	ds_write_b16_d16_hi v8, v0 offset:6912
	v_bfe_u32 v0, v7, 16, 1
	v_add3_u32 v0, v7, v0, s33
	v_ashrrev_i32_e32 v2, 1, v226
	ds_write_b16_d16_hi v8, v0 offset:6976
	v_bfe_u32 v0, v5, 16, 1
	v_and_b32_e32 v2, 0xffffffe0, v2
	v_add3_u32 v0, v5, v0, s33
	v_add_u32_e32 v2, s64, v2
	ds_write_b16_d16_hi v8, v0 offset:7040
	v_bfe_u32 v0, v4, 16, 1
	v_ashrrev_i32_e32 v3, 31, v2
	v_add3_u32 v0, v4, v0, s33
	v_lshlrev_b64 v[2:3], 12, v[2:3]
	ds_write_b16_d16_hi v8, v0 offset:7104
	v_lshlrev_b32_e32 v0, 4, v6
	v_lshl_add_u64 v[2:3], s[6:7], 0, v[2:3]
	v_and_b32_e32 v0, 0xf0, v0
	v_lshl_add_u64 v[2:3], s[10:11], 1, v[2:3]
	v_bfe_u32 v10, v6, 4, 2
	v_add_u32_e32 v11, v9, v0
	s_waitcnt lgkmcnt(0)
	v_lshl_add_u64 v[6:7], v[2:3], 0, v[0:1]
	v_lshl_add_u32 v0, v10, 8, v11
	ds_read_b128 v[2:5], v0
	v_lshlrev_b32_e32 v0, 12, v10
	v_lshl_add_u64 v[8:9], v[6:7], 0, v[0:1]
	v_or_b32_e32 v0, 4, v10
	v_readlane_b32 s0, v254, 31
	s_waitcnt lgkmcnt(0)
	flat_store_dwordx4 v[8:9], v[2:5] offset:3072
	s_add_i32 s40, s40, s0
	s_cmpk_gt_i32 s41, 0xff
	v_lshl_add_u32 v2, v0, 8, v11
	ds_read_b128 v[2:5], v2
	v_lshlrev_b32_e32 v0, 12, v0
	v_lshl_add_u64 v[8:9], v[6:7], 0, v[0:1]
	v_or_b32_e32 v0, 8, v10
	s_waitcnt lgkmcnt(0)
	flat_store_dwordx4 v[8:9], v[2:5] offset:3072
	s_nop 1
	v_lshl_add_u32 v2, v0, 8, v11
	ds_read_b128 v[2:5], v2
	v_lshlrev_b32_e32 v0, 12, v0
	v_lshl_add_u64 v[8:9], v[6:7], 0, v[0:1]
	v_or_b32_e32 v0, 12, v10
	s_waitcnt lgkmcnt(0)
	flat_store_dwordx4 v[8:9], v[2:5] offset:3072
	s_nop 1
	v_lshl_add_u32 v2, v0, 8, v11
	ds_read_b128 v[2:5], v2
	v_lshlrev_b32_e32 v0, 12, v0
	v_lshl_add_u64 v[8:9], v[6:7], 0, v[0:1]
	v_or_b32_e32 v0, 16, v10
	s_waitcnt lgkmcnt(0)
	flat_store_dwordx4 v[8:9], v[2:5] offset:3072
	s_nop 1
	v_lshl_add_u32 v2, v0, 8, v11
	ds_read_b128 v[2:5], v2
	v_lshlrev_b32_e32 v0, 12, v0
	v_lshl_add_u64 v[8:9], v[6:7], 0, v[0:1]
	v_or_b32_e32 v0, 20, v10
	s_waitcnt lgkmcnt(0)
	flat_store_dwordx4 v[8:9], v[2:5] offset:3072
	s_nop 1
	v_lshl_add_u32 v2, v0, 8, v11
	ds_read_b128 v[2:5], v2
	v_lshlrev_b32_e32 v0, 12, v0
	v_lshl_add_u64 v[8:9], v[6:7], 0, v[0:1]
	v_or_b32_e32 v0, 24, v10
	s_waitcnt lgkmcnt(0)
	flat_store_dwordx4 v[8:9], v[2:5] offset:3072
	s_nop 1
	v_lshl_add_u32 v2, v0, 8, v11
	ds_read_b128 v[2:5], v2
	v_lshlrev_b32_e32 v0, 12, v0
	v_lshl_add_u64 v[8:9], v[6:7], 0, v[0:1]
	v_or_b32_e32 v0, 28, v10
	s_waitcnt lgkmcnt(0)
	flat_store_dwordx4 v[8:9], v[2:5] offset:3072
	s_nop 1
	v_lshl_add_u32 v2, v0, 8, v11
	ds_read_b128 v[2:5], v2
	v_lshlrev_b32_e32 v0, 12, v0
	v_lshl_add_u64 v[6:7], v[6:7], 0, v[0:1]
	s_waitcnt lgkmcnt(0)
	flat_store_dwordx4 v[6:7], v[2:5] offset:3072
	s_waitcnt lgkmcnt(0)
	s_cbranch_scc1 .LBB0_380
; template <int NQ, int MODE> ...
;     ...
;     for (int i = 0; i < 2; ++i) { const int p = wid + 8 * i, row = 4 * p + (lane >> 4), cbs = (lane & 15) ^ (row & 15); voK1[i] = (unsigned)(row * ldk0 + cbs * 8) * 2u; }
;     { const int row = 8 * wid + (lane >> 3), cbs = (lane & 7) ^ ((row >> 1) & 7); voK2 = (unsigned)(row * ldk2 + cbs * 8) * 2u; }
; #pragma unroll
;     for (int i = 0; i < 2; ++i) { const int p = wid + 8 * i, sub = 2 * p + (lane >> 5), kk = ((sub >> 2) << 3) | ((lane & 31) >> 2);
;         const int k = kk, c = (sub & 3) * 32 + (lane & 3) * 8; voV[i] = (unsigned)(k * ldv + c) * 2u; }
;     const char* gK1 = (const char*)(K0 + (size_t)kt0 * KVBLK * ldk0); const size_t stK1 = (size_t)KVBLK * ldk0 * 2;
;     const char* gK2 = (const char*)(K2 + (size_t)kt0 * KVBLK * ldk2); const size_t stK2 = (size_t)KVBLK * ldk2 * 2;
;     const char* gV = (const char*)(Vh + (size_t)kt0 * KVBLK * ldv); const size_t stV = (size_t)KVBLK * ldv * 2;
;     LAS unsigned char* K3 = (LAS unsigned char*)K_lds; LAS unsigned char* V3 = (LAS unsigned char*)V_lds;
;     ...
;     const char* pK1a = gK1 + voK1[0]; const char* pK1b = gK1 + voK1[1]; const char* pK2p = gK2 + voK2; const char* pVa = gV + voV[0]; const char* pVb = gV + voV[1];
;     ...
;     bf16x8 qr[NQ];
;     const bf16_t* Qw = Qb + (long)(wid * QBLK + r32) * ldq + hi * 8;
;     __syncthreads();
; #pragma unroll
;     for (int d0 = 0; d0 < NQ; ++d0) qr[d0] = *reinterpret_cast<const bf16x8*>(Qw + d0 * 16);
;     DMA_K(0, 0); DMA_V(0, 0); DMA_K(1, 1);
;     const int lo1 = (hi ^ (r32 & 1)) << 4, s3 = (r32 >> 1) & 7, b1_ = r32 * 256 + lo1;
;     const int kb1[2] = {b1_, s3};
;     const int lo2 = (hi ^ ((r32 >> 1) & 1)) << 4, s2 = (r32 >> 2) & 3, b2_ = r32 * 128 + lo2;
;     const int kb2[2] = {b2_, s2};
;     const int vb0 = (int)(uintptr_t)V_lds + v_rd_base(lane);
;     const int kl0 = (int)(uintptr_t)K_lds;
; __global__ void __launch_bounds__(NTHR, 2) mega_fwd(Args a) {
;     ...
;         for (int u = vcu; u < 256; u += G) { PH
;             const int hd = u >> 6, blk = u & 63, q0 = blk * 256;
;             f32x16 o[4];
;     ...
;             float* lut = (float*)(lds + att::OFF_LUT);
;             { UNIT_IDS att::attn_core<8, 0>(P + (size_t)q0 * INP + C_AQ + hd * 128, INP, P + C_AK + (hd >> 1) * 128, INP, nullptr, 0, P + C_AV + (hd >> 1) * 128, INP, 0, SEQ / 64, q0, nullptr, 0.f, 0.f, 0.f, 0.f, (char*)lds, o, wave_s);
.LBB0_384:
	s_bfe_u32 s83, s40, 0x60008
	s_lshl_b32 s0, s41, 8
	s_lshl_b32 s37, s83, 8
	s_and_b32 s64, s0, 0x3f00
	s_max_i32 s39, s37, 0x80
	s_mov_b64 s[28:29], s[60:61]
	s_ashr_i32 s38, s41, 6
	s_mul_i32 s0, s64, 0x2200
	s_add_u32 s0, s28, s0
	s_addc_u32 s1, s29, 0
	s_mov_b32 s30, s84
	s_add_u32 s82, s0, 0x12000000
	v_mbcnt_lo_u32_b32 v192, -1, 0
	v_mbcnt_hi_u32_b32 v192, -1, v192
	s_addc_u32 s73, s1, 0
	s_lshl_b32 s10, s38, 7
	v_mbcnt_lo_u32_b32 v10, -1, 0
	v_mbcnt_hi_u32_b32 v10, -1, v10
	s_ashr_i32 s11, s10, 31
	v_bfe_u32 v0, v10, 4, 2
	v_or_b32_e32 v2, s50, v0
	v_bitop3_b32 v0, v0, v10, s50 bitop3:0x36
	s_lshl_b64 s[34:35], s[10:11], 1
	v_mul_lo_u32 v2, v2, s49
	v_lshlrev_b32_e32 v0, 3, v0
	s_movk_i32 s6, 0x78
	s_add_u32 s78, s82, s34
	v_bfe_u32 v11, v10, 5, 1
	v_and_or_b32 v0, v0, s6, v2
	v_readlane_b32 s6, v254, 34
	v_lshlrev_b32_e32 v5, 3, v10
	s_addc_u32 s79, s73, s35
	v_and_b32_e32 v64, 31, v10
	v_bfe_u32 v3, v10, 2, 3
	v_or_b32_e32 v4, s6, v11
	v_and_b32_e32 v5, 24, v5
	v_readlane_b32 s6, v254, 35
	v_lshl_or_b32 v5, v4, 5, v5
	v_or_b32_e32 v12, s80, v64
	v_or_b32_e32 v4, s6, v3
	v_readlane_b32 s6, v254, 0
	v_mov_b64_e32 v[8:9], s[78:79]
	v_lshlrev_b32_e32 v48, 4, v11
	v_or_b32_e32 v3, s6, v3
	v_mad_u64_u32 v[8:9], s[6:7], v12, s69, v[8:9]
	v_mov_b32_e32 v49, v1
	v_lshl_add_u64 v[8:9], v[8:9], 0, v[48:49]
	s_barrier
	flat_load_dwordx4 v[172:175], v[8:9]
	flat_load_dwordx4 v[168:171], v[8:9] offset:32
	flat_load_dwordx4 v[164:167], v[8:9] offset:64
	flat_load_dwordx4 v[160:163], v[8:9] offset:96
	flat_load_dwordx4 v[156:159], v[8:9] offset:128
	flat_load_dwordx4 v[152:155], v[8:9] offset:160
	flat_load_dwordx4 v[148:151], v[8:9] offset:192
	flat_load_dwordx4 v[144:147], v[8:9] offset:224
	s_and_b32 s0, s41, 0xffffff80
	s_ashr_i32 s1, s0, 31
	s_lshl_b64 s[56:57], s[0:1], 1
	s_add_u32 s4, s28, s56
	s_addc_u32 s5, s29, s57
	s_add_u32 s0, s4, 0x12000400
	s_addc_u32 s1, s5, 0
	s_add_u32 s4, s4, 0x12000600
	v_mul_lo_u32 v3, v3, s49
	s_mov_b32 m0, s81
	s_addc_u32 s5, s5, 0
	v_lshlrev_b32_e32 v0, 1, v0
	v_or_b32_e32 v3, v5, v3
	s_add_i32 s67, s81, 0x2000
	v_add_u32_e32 v2, 0x44000, v0
	v_lshlrev_b32_e32 v6, 1, v3
	v_mov_b32_e32 v3, v1
	global_load_lds_dwordx4 v0, s[0:1]
	s_mov_b32 m0, s67
	v_mul_lo_u32 v4, v4, s49
	v_lshl_add_u64 v[54:55], s[0:1], 0, v[0:1]
	v_lshl_add_u64 v[50:51], s[0:1], 0, v[2:3]
	global_load_lds_dwordx4 v2, s[0:1]
	s_add_i32 s31, 0, 0x12000
	v_readlane_b32 s0, v254, 47
	v_or_b32_e32 v4, v5, v4
	s_add_i32 s14, s31, s0
	v_lshlrev_b32_e32 v4, 1, v4
	s_mov_b32 m0, s14
	s_add_i32 s15, s14, 0x2000
	global_load_lds_dwordx4 v4, s[4:5]
	s_mov_b32 m0, s15
	s_add_i32 s70, s81, 0x4000
	v_lshl_add_u64 v[2:3], v[54:55], 0, s[74:75]
	global_load_lds_dwordx4 v6, s[4:5]
	s_mov_b32 m0, s70
	s_add_i32 s85, s81, 0x6000
	v_lshl_add_u64 v[8:9], v[50:51], 0, s[74:75]
	global_load_lds_dwordx4 v[2:3], off
	s_mov_b32 m0, s85
	s_add_i32 s87, s81, 0x8000
	global_load_lds_dwordx4 v[8:9], off
	v_mov_b32_e32 v5, v1
	s_waitcnt vmcnt(2) lgkmcnt(0)
	s_barrier
	v_lshl_add_u64 v[8:9], v[54:55], 0, s[46:47]
	s_mov_b32 m0, s87
	s_add_i32 s86, s81, 0xa000
	v_mov_b32_e32 v7, v1
	v_lshl_add_u64 v[56:57], s[4:5], 0, v[4:5]
	v_bitop3_b32 v0, v11, v10, 1 bitop3:0x78
	v_lshlrev_b32_e32 v11, 8, v64
	v_lshlrev_b32_e32 v12, 4, v10
	v_lshl_add_u64 v[2:3], v[50:51], 0, s[46:47]
	global_load_lds_dwordx4 v[8:9], off
	s_mov_b32 m0, s86
	s_add_i32 s71, s81, 0x16000
	v_lshl_add_u64 v[52:53], s[4:5], 0, v[6:7]
	v_lshl_add_u64 v[4:5], v[56:57], 0, s[74:75]
	global_load_lds_dwordx4 v[2:3], off
	s_mov_b32 m0, s71
	s_add_i32 s72, s81, 0x18000
	v_lshl_or_b32 v49, v0, 4, v11
	v_and_b32_e32 v65, 0xe0, v12
	v_lshl_add_u64 v[6:7], v[52:53], 0, s[74:75]
	global_load_lds_dwordx4 v[4:5], off
	s_mov_b32 m0, s72
	v_mov_b32_e32 v16, v1
	v_mov_b32_e32 v17, v1
	v_mov_b32_e32 v18, v1
	v_mov_b32_e32 v19, v1
	v_mov_b32_e32 v20, v1
	v_mov_b32_e32 v21, v1
	v_mov_b32_e32 v22, v1
	v_mov_b32_e32 v23, v1
	v_mov_b32_e32 v24, v1
	v_mov_b32_e32 v25, v1
	v_mov_b32_e32 v26, v1
	v_mov_b32_e32 v27, v1
	v_mov_b32_e32 v28, v1
	v_mov_b32_e32 v29, v1
	v_mov_b32_e32 v30, v1
	v_mov_b32_e32 v31, v1
	v_add3_u32 v0, 0, v65, v49
	global_load_lds_dwordx4 v[6:7], off
	ds_read_b128 v[2:5], v0
	ds_read_b128 v[6:9], v0 offset:8192
	s_waitcnt vmcnt(0) lgkmcnt(0)
	v_mfma_f32_32x32x16_bf16 v[32:47], v[2:5], v[172:175], v[16:31]
	v_bitop3_b32 v215, v12, 32, v221 bitop3:0x6c
	v_add3_u32 v0, 0, v215, v49
	v_bitop3_b32 v214, v12, 64, v221 bitop3:0x6c
	v_bitop3_b32 v213, v12, s45, v221 bitop3:0x6c
	s_movk_i32 s0, 0x80
	v_bitop3_b32 v212, v12, s0, v221 bitop3:0x6c
	s_movk_i32 s0, 0xa0
	v_mfma_f32_32x32x16_bf16 v[16:31], v[6:9], v[172:175], v[16:31]
	ds_read_b128 v[2:5], v0
	ds_read_b128 v[6:9], v0 offset:8192
	v_add3_u32 v0, 0, v214, v49
	v_bitop3_b32 v199, v12, s0, v221 bitop3:0x6c
	v_and_b32_e32 v66, 63, v10
	s_movk_i32 s0, 0xc0
	v_bitop3_b32 v198, v12, s0, v221 bitop3:0x6c
	v_add3_u32 v11, 0, v198, v49
	s_waitcnt lgkmcnt(0)
	v_mfma_f32_32x32x16_bf16 v[16:31], v[6:9], v[168:171], v[16:31]
	s_movk_i32 s0, 0xe0
	v_bitop3_b32 v197, v12, s0, v12 bitop3:0xc
	s_mov_b32 m0, s81
	v_lshl_add_u64 v[14:15], v[50:51], 0, s[76:77]
	s_add_i32 s65, s81, 0x1a000
	v_lshl_add_u64 v[62:63], v[56:57], 0, s[46:47]
	s_add_i32 s66, s81, 0x1c000
	v_mfma_f32_32x32x16_bf16 v[32:47], v[2:5], v[168:171], v[32:47]
	ds_read_b128 v[2:5], v0
	ds_read_b128 v[6:9], v0 offset:8192
	v_add3_u32 v0, 0, v213, v49
	s_mov_b64 s[4:5], 0x220000
	s_mov_b32 s12, 1
	s_mov_b32 s16, 0
	v_lshl_add_u64 v[184:185], v[54:55], 0, s[4:5]
	v_lshl_add_u64 v[186:187], v[56:57], 0, s[76:77]
	s_waitcnt lgkmcnt(0)
	v_mfma_f32_32x32x16_bf16 v[16:31], v[6:9], v[164:167], v[16:31]
	v_mfma_f32_32x32x16_bf16 v[32:47], v[2:5], v[164:167], v[32:47]
	ds_read_b128 v[2:5], v0
	ds_read_b128 v[6:9], v0 offset:8192
	v_add3_u32 v0, 0, v212, v49
	s_waitcnt lgkmcnt(0)
	v_mfma_f32_32x32x16_bf16 v[16:31], v[6:9], v[160:163], v[16:31]
	v_mfma_f32_32x32x16_bf16 v[32:47], v[2:5], v[160:163], v[32:47]
	ds_read_b128 v[2:5], v0
	ds_read_b128 v[6:9], v0 offset:8192
	v_add3_u32 v0, 0, v199, v49
	s_waitcnt lgkmcnt(0)
	v_mfma_f32_32x32x16_bf16 v[16:31], v[6:9], v[156:159], v[16:31]
	v_mfma_f32_32x32x16_bf16 v[32:47], v[2:5], v[156:159], v[32:47]
	ds_read_b128 v[2:5], v0
	ds_read_b128 v[6:9], v0 offset:8192
	v_lshlrev_b32_e32 v0, 3, v66
	s_waitcnt lgkmcnt(0)
	v_mfma_f32_32x32x16_bf16 v[16:31], v[6:9], v[152:155], v[16:31]
	v_and_b32_e32 v6, 0xc0, v12
	v_lshlrev_b32_e32 v7, 1, v10
	v_and_or_b32 v6, v0, 24, v6
	v_and_b32_e32 v7, 32, v7
	v_and_b32_e32 v0, 0x100, v0
	v_or3_b32 v67, v6, v7, v0
	ds_read_b128 v[6:9], v11 offset:8192
	v_mfma_f32_32x32x16_bf16 v[32:47], v[2:5], v[152:155], v[32:47]
	ds_read_b128 v[2:5], v11
	v_mov_b32_e32 v0, v1
	s_waitcnt lgkmcnt(1)
	v_mfma_f32_32x32x16_bf16 v[16:31], v[6:9], v[148:151], v[16:31]
	v_add3_u32 v6, 0, v197, v49
	ds_read_b128 v[10:13], v6
	ds_read_b128 v[58:61], v6 offset:8192
	s_waitcnt vmcnt(4) lgkmcnt(0)
	s_barrier
; #define DMA_K(t, st) do { if (HAS1) { GLDS(pK1a, K3 + (st) * SHM_KT + wid * 1024); GLDS(pK1b, K3 + (st) * SHM_KT + (wid + 8) * 1024); pK1a += stK1; pK1b += stK1; } \
;     if (HAS2) { GLDS(pK2p, K3 + (st) * SHM_KT + SHM_K1 + wid * 1024); pK2p += stK2; } } while (0)
; #define DMA_V(t, st) do { GLDS(pVa, V3 + (st) * SHM_V + wid * 1024); GLDS(pVb, V3 + (st) * SHM_V + (wid + 8) * 1024); pVa += stV; pVb += stV; } while (0)
; #define WAITB(n) do { if ((n) == 0) WAIT_BAR(0); else if ((n) == 1) WAIT_BAR(1); else if ((n) == 2) WAIT_BAR(2); else if ((n) == 3) WAIT_BAR(3); else if ((n) == 4) WAIT_BAR(4); else WAIT_BAR(5); } while (0)
; template <int MODE, bool FIRST, bool FOLD>
; __device__ __forceinline__ bool partialSM(f32x16& p0, f32x16& p1, float& m_reg, float& alpha, int relbase, bool near, const float* lut, float cb) {
;     ...
;     float pmax = p0[0];
; #pragma unroll
;     for (int r = 1; r < 16; ++r) pmax = fmaxf(pmax, p0[r]);
; #pragma unroll
;     for (int r = 0; r < 16; ++r) pmax = fmaxf(pmax, p1[r]);
;     { auto rr = __builtin_amdgcn_permlane32_swap(__float_as_uint(pmax), __float_as_uint(pmax), false, false);
;       pmax = fmaxf(__uint_as_float(rr[0]), __uint_as_float(rr[1])); }
;     bool resc;
;     if (FIRST && MODE != 2) resc = true; else resc = __any(pmax > THR2);
;     if (__builtin_expect(resc, FIRST && MODE != 2)) {
;         const float delta = (FIRST && MODE != 2) ? pmax : fmaxf(pmax, 0.f);
;         m_reg += delta; alpha = (FIRST && MODE != 2) ? 1.f : __builtin_amdgcn_exp2f(-delta);
; #pragma unroll
;         for (int r = 0; r < 16; ++r) { p0[r] -= delta; p1[r] -= delta; }
;     } else alpha = 1.f;
; #pragma unroll
;     for (int r = 0; r < 16; ++r) p0[r] = __builtin_amdgcn_exp2f(p0[r]);
; template <int NQ, int MODE> ...
;     ...
;     f32x16 cinit = f32x16{}; float cur_cb = 0.f; bool dirty = true;
;     ...
;     f32x16 pA0, pA1, pB0, pB1; float alA, alB; bool rsA, rsB; bf16x8 pa0, pa1, pa2, pa3;
;     WAITB(NLK);
;     if (2 < NT) DMA_K(2, 2); DMA_V(1, 1);
;     CINIT(0);
;     qkt<NQ>(pA0, pA1, K_lds, kb1, kb2, qr, cinit); { TILEP(0); (void)cbT; rsA = partialSM<MODE, true, FOLD>(pA0, pA1, m_reg, alA, relb, nearT, lut, cbT); dirty |= rsA; }
;     l_reg *= alA;
;     if (2 < NT) WAITB(NL); else WAITB(NLV);
;     ...
;     int kc = 1, vp = 0;
;     ...
;     bf16x8 kfp0 = {}, kfp1 = {};
;     ...
;     DMA_K(3, 0); DMA_V(2, 2);
;     KPRE(kc); CINIT(1);
	v_mov_b32_e32 v6, v1
	v_mov_b32_e32 v7, v1
	v_mov_b32_e32 v8, v1
	v_mov_b32_e32 v9, v1
	s_waitcnt lgkmcnt(2)
	v_mfma_f32_32x32x16_bf16 v[32:47], v[2:5], v[148:151], v[32:47]
	v_lshl_add_u64 v[2:3], v[54:55], 0, s[76:77]
	global_load_lds_dwordx4 v[2:3], off
	s_mov_b32 m0, s67
	v_lshl_add_u64 v[4:5], v[52:53], 0, s[46:47]
	global_load_lds_dwordx4 v[14:15], off
	s_mov_b32 m0, s65
	s_waitcnt lgkmcnt(0)
	v_mfma_f32_32x32x16_bf16 v[32:47], v[10:13], v[144:147], v[32:47]
	global_load_lds_dwordx4 v[62:63], off
	s_mov_b32 m0, s66
	v_mov_b32_e32 v2, v1
	global_load_lds_dwordx4 v[4:5], off
	v_mov_b32_e32 v3, v1
	v_mfma_f32_32x32x16_bf16 v[16:31], v[58:61], v[144:147], v[16:31]
	s_nop 5
	v_max_f32_e32 v58, v33, v33
	v_max_f32_e32 v59, v32, v32
	v_max_f32_e32 v58, v59, v58
	v_max3_f32 v58, v58, v34, v35
	v_max3_f32 v58, v58, v36, v37
	v_max3_f32 v58, v58, v38, v39
	v_max3_f32 v58, v58, v40, v41
	v_max3_f32 v58, v58, v42, v43
	v_max3_f32 v58, v58, v44, v45
	v_max3_f32 v58, v58, v46, v47
	v_max3_f32 v58, v58, v16, v17
	v_max3_f32 v58, v58, v18, v19
	v_max3_f32 v58, v58, v20, v21
	v_max3_f32 v58, v58, v22, v23
	v_max3_f32 v58, v58, v24, v25
	v_max3_f32 v58, v58, v26, v27
	v_max3_f32 v58, v58, v28, v29
	v_max3_f32 v58, v58, v30, v31
	v_mov_b32_e32 v59, v58
	s_nop 1
	v_permlane32_swap_b32_e32 v58, v59
	v_max_f32_e32 v59, v59, v59
	v_max_f32_e32 v58, v58, v58
	v_max_f32_e32 v58, v58, v59
	v_sub_f32_e32 v32, v32, v58
	v_exp_f32_e32 v231, v32
	v_or_b32_e32 v32, v49, v65
	v_add_u32_e32 v216, 0, v32
	v_sub_f32_e32 v33, v33, v58
	v_sub_f32_e32 v34, v34, v58
	v_sub_f32_e32 v35, v35, v58
	v_sub_f32_e32 v36, v36, v58
	v_sub_f32_e32 v37, v37, v58
	v_sub_f32_e32 v38, v38, v58
	v_sub_f32_e32 v39, v39, v58
	v_sub_f32_e32 v40, v40, v58
	v_sub_f32_e32 v41, v41, v58
	v_sub_f32_e32 v42, v42, v58
	v_sub_f32_e32 v43, v43, v58
	v_sub_f32_e32 v44, v44, v58
	v_sub_f32_e32 v45, v45, v58
	v_sub_f32_e32 v46, v46, v58
	v_sub_f32_e32 v47, v47, v58
	ds_read_b128 v[180:183], v216 offset:16384
	ds_read_b128 v[176:179], v216 offset:24576
	v_exp_f32_e32 v232, v33
	v_exp_f32_e32 v233, v34
	v_exp_f32_e32 v235, v35
	v_exp_f32_e32 v234, v36
	v_exp_f32_e32 v236, v37
	v_exp_f32_e32 v237, v38
	v_exp_f32_e32 v238, v39
	v_exp_f32_e32 v200, v40
	v_exp_f32_e32 v201, v41
	v_exp_f32_e32 v202, v42
	v_exp_f32_e32 v225, v43
	v_exp_f32_e32 v203, v44
	v_exp_f32_e32 v228, v45
	v_exp_f32_e32 v229, v46
	v_exp_f32_e32 v230, v47
	v_add_f32_e32 v217, 0, v58
	v_mov_b32_e32 v4, v1
	v_mov_b32_e32 v5, v1
	v_mov_b32_e32 v10, v1
	v_mov_b32_e32 v11, v1
	v_mov_b32_e32 v12, v1
	v_mov_b32_e32 v13, v1
	v_mov_b32_e32 v14, v1
	v_mov_b32_e32 v15, v1
	s_cmp_lg_u32 s31, -1
	s_cselect_b32 s0, s31, 0
	s_cmp_lg_u32 0, -1
	v_add_u32_e32 v196, s0, v67
	s_cselect_b32 s0, 0, 0
	v_sub_f32_e32 v80, 0, v217
	v_sub_f32_e32 v111, v31, v58
	v_sub_f32_e32 v110, v30, v58
	v_sub_f32_e32 v109, v29, v58
	v_sub_f32_e32 v108, v28, v58
	v_sub_f32_e32 v107, v27, v58
	v_sub_f32_e32 v106, v26, v58
	v_sub_f32_e32 v105, v25, v58
	v_sub_f32_e32 v104, v24, v58
	v_sub_f32_e32 v103, v23, v58
	v_sub_f32_e32 v102, v22, v58
	v_sub_f32_e32 v101, v21, v58
	v_sub_f32_e32 v100, v20, v58
	v_sub_f32_e32 v99, v19, v58
	v_sub_f32_e32 v98, v18, v58
	v_sub_f32_e32 v97, v17, v58
	v_sub_f32_e32 v96, v16, v58
	v_lshl_add_u64 v[188:189], v[50:51], 0, s[4:5]
	v_lshl_add_u64 v[190:191], v[52:53], 0, s[76:77]
	v_add_u32_e32 v226, s0, v49
	v_cmp_gt_u32_e64 s[4:5], 32, v66
	v_lshl_add_u32 v194, v64, 2, s97
	v_add_u32_e32 v193, s97, v48
	v_mov_b64_e32 v[30:31], v[14:15]
	v_mov_b64_e32 v[46:47], v[14:15]
	v_mov_b64_e32 v[62:63], v[14:15]
	v_mov_b64_e32 v[78:79], v[14:15]
	s_mov_b64 s[90:91], 0x220000
	v_mov_b32_e32 v81, v80
	v_mov_b32_e32 v82, v80
	v_mov_b32_e32 v83, v80
	v_mov_b32_e32 v84, v80
	v_mov_b32_e32 v85, v80
	v_mov_b32_e32 v86, v80
	v_mov_b32_e32 v87, v80
	v_mov_b32_e32 v88, v80
	v_mov_b32_e32 v89, v80
	v_mov_b32_e32 v90, v80
	v_mov_b32_e32 v91, v80
	v_mov_b32_e32 v92, v80
	v_mov_b32_e32 v93, v80
	v_mov_b32_e32 v94, v80
	v_mov_b32_e32 v95, v80
	v_mov_b32_e32 v195, 0
	s_movk_i32 s17, 0xff04
	v_mov_b64_e32 v[28:29], v[12:13]
	v_mov_b64_e32 v[26:27], v[10:11]
	v_mov_b64_e32 v[24:25], v[8:9]
	v_mov_b64_e32 v[22:23], v[6:7]
	v_mov_b64_e32 v[20:21], v[4:5]
	v_mov_b64_e32 v[18:19], v[2:3]
	v_mov_b64_e32 v[16:17], v[0:1]
	v_mov_b64_e32 v[44:45], v[12:13]
	v_mov_b64_e32 v[42:43], v[10:11]
	v_mov_b64_e32 v[40:41], v[8:9]
	v_mov_b64_e32 v[38:39], v[6:7]
	v_mov_b64_e32 v[36:37], v[4:5]
	v_mov_b64_e32 v[34:35], v[2:3]
	v_mov_b64_e32 v[32:33], v[0:1]
	v_mov_b64_e32 v[60:61], v[12:13]
	v_mov_b64_e32 v[58:59], v[10:11]
	v_mov_b64_e32 v[56:57], v[8:9]
	v_mov_b64_e32 v[54:55], v[6:7]
	v_mov_b64_e32 v[52:53], v[4:5]
	v_mov_b64_e32 v[50:51], v[2:3]
	v_mov_b64_e32 v[48:49], v[0:1]
	v_mov_b64_e32 v[76:77], v[12:13]
	v_mov_b64_e32 v[74:75], v[10:11]
	v_mov_b64_e32 v[72:73], v[8:9]
	v_mov_b64_e32 v[70:71], v[6:7]
	v_mov_b64_e32 v[68:69], v[4:5]
	v_mov_b64_e32 v[66:67], v[2:3]
	v_mov_b64_e32 v[64:65], v[0:1]

; template <int MODE, bool FIRST, bool FOLD>
; __device__ __forceinline__ bool partialSM(f32x16& p0, f32x16& p1, float& m_reg, float& alpha, int relbase, bool near, const float* lut, float cb) {
;     ...
;     float pmax = p0[0];
; #pragma unroll
;     for (int r = 1; r < 16; ++r) pmax = fmaxf(pmax, p0[r]);
; #pragma unroll
;     for (int r = 0; r < 16; ++r) pmax = fmaxf(pmax, p1[r]);
;     { auto rr = __builtin_amdgcn_permlane32_swap(__float_as_uint(pmax), __float_as_uint(pmax), false, false);
;       pmax = fmaxf(__uint_as_float(rr[0]), __uint_as_float(rr[1])); }
;     bool resc;
;     if (FIRST && MODE != 2) resc = true; else resc = __any(pmax > THR2);
.LBB0_395:
	s_add_i32 s6, s12, 1
	s_cmp_lt_i32 s12, 2
	s_cselect_b32 s19, s6, 0
	s_lshl_b32 s20, s19, 14
	v_add_u32_e32 v2, s20, v216
	ds_read_b128 v[6:9], v2
	ds_read_b128 v[2:5], v2 offset:8192
	v_max_f32_e32 v10, v129, v129
	v_max_f32_e32 v11, v128, v128
	v_max_f32_e32 v10, v11, v10
	v_max_f32_e32 v11, v112, v113
	v_max3_f32 v10, v10, v130, v131
	v_max3_f32 v11, v11, v114, v115
	v_max3_f32 v10, v10, v132, v133
	v_max3_f32 v11, v11, v116, v117
	v_max3_f32 v10, v10, v134, v135
	v_max3_f32 v11, v11, v118, v119
	v_max3_f32 v10, v10, v136, v137
	v_max3_f32 v11, v11, v120, v121
	v_max3_f32 v10, v10, v138, v139
	v_max3_f32 v11, v11, v122, v123
	v_max3_f32 v10, v10, v140, v141
	v_max3_f32 v11, v11, v124, v125
	v_max3_f32 v10, v10, v142, v143
	v_max3_f32 v11, v11, v126, v127
	v_max_f32_e32 v10, v10, v11
	v_mov_b32_e32 v11, v10
	s_nop 1
	v_permlane32_swap_b32_e32 v10, v11
	v_max_f32_e32 v11, v11, v11
	v_max_f32_e32 v10, v10, v10
	v_max_f32_e32 v10, v10, v11
	v_cmp_lt_f32_e32 vcc, s51, v10
	s_cmp_lg_u64 vcc, 0
	s_cselect_b64 s[12:13], -1, 0
	v_mov_b32_e32 v14, 1.0
	s_cbranch_vccnz .LBB0_409
	v_cndmask_b32_e64 v10, 0, 1, s[12:13]
	v_cmp_ne_u32_e64 s[6:7], 1, v10
	s_andn2_b64 vcc, exec, s[12:13]
	s_cbranch_vccz .LBB0_410

; template <int MODE, bool FIRST, bool FOLD>
; __device__ __forceinline__ bool partialSM(f32x16& p0, f32x16& p1, float& m_reg, float& alpha, int relbase, bool near, const float* lut, float cb) {
;     ...
;     float pmax = p0[0];
; #pragma unroll
;     for (int r = 1; r < 16; ++r) pmax = fmaxf(pmax, p0[r]);
; #pragma unroll
;     for (int r = 0; r < 16; ++r) pmax = fmaxf(pmax, p1[r]);
;     { auto rr = __builtin_amdgcn_permlane32_swap(__float_as_uint(pmax), __float_as_uint(pmax), false, false);
;       pmax = fmaxf(__uint_as_float(rr[0]), __uint_as_float(rr[1])); }
;     bool resc;
;     if (FIRST && MODE != 2) resc = true; else resc = __any(pmax > THR2);
.LBB0_406:
	s_add_i32 s6, s19, 1
	s_cmp_lt_i32 s19, 2
	s_cselect_b32 s12, s6, 0
	s_lshl_b32 s19, s12, 14
	v_add_u32_e32 v2, s19, v216
	ds_read_b128 v[180:183], v2
	ds_read_b128 v[176:179], v2 offset:8192
	v_max_f32_e32 v2, v129, v129
	v_max_f32_e32 v3, v128, v128
	v_max_f32_e32 v2, v3, v2
	v_max_f32_e32 v3, v96, v97
	v_max3_f32 v2, v2, v130, v131
	v_max3_f32 v3, v3, v98, v99
	v_max3_f32 v2, v2, v132, v133
	v_max3_f32 v3, v3, v100, v101
	v_max3_f32 v2, v2, v134, v135
	v_max3_f32 v3, v3, v102, v103
	v_max3_f32 v2, v2, v136, v137
	v_max3_f32 v3, v3, v104, v105
	v_max3_f32 v2, v2, v138, v139
	v_max3_f32 v3, v3, v106, v107
	v_max3_f32 v2, v2, v140, v141
	v_max3_f32 v3, v3, v108, v109
	v_max3_f32 v2, v2, v142, v143
	v_max3_f32 v3, v3, v110, v111
	v_max_f32_e32 v2, v2, v3
	v_mov_b32_e32 v3, v2
	s_nop 1
	v_permlane32_swap_b32_e32 v2, v3
	v_max_f32_e32 v3, v3, v3
	v_max_f32_e32 v2, v2, v2
	v_max_f32_e32 v3, v2, v3
	v_cmp_lt_f32_e32 vcc, s51, v3
	s_cmp_lg_u64 vcc, 0
	s_cselect_b64 s[6:7], -1, 0
	v_mov_b32_e32 v2, 1.0
	s_cbranch_vccnz .LBB0_414
	s_andn2_b64 vcc, exec, s[6:7]
	s_cbranch_vccz .LBB0_415

; template <int MODE, bool FIRST, bool FOLD>
; __device__ __forceinline__ bool partialSM(f32x16& p0, f32x16& p1, float& m_reg, float& alpha, int relbase, bool near, const float* lut, float cb) {
;     ...
;     float pmax = p0[0];
; #pragma unroll
;     for (int r = 1; r < 16; ++r) pmax = fmaxf(pmax, p0[r]);
; #pragma unroll
;     for (int r = 0; r < 16; ++r) pmax = fmaxf(pmax, p1[r]);
;     { auto rr = __builtin_amdgcn_permlane32_swap(__float_as_uint(pmax), __float_as_uint(pmax), false, false);
;       pmax = fmaxf(__uint_as_float(rr[0]), __uint_as_float(rr[1])); }
;     bool resc;
;     if (FIRST && MODE != 2) resc = true; else resc = __any(pmax > THR2);
.LBB0_711:
	v_max_f32_e32 v0, v161, v161
	v_max_f32_e32 v10, v160, v160
	v_max_f32_e32 v0, v10, v0
	v_max_f32_e32 v10, v144, v145
	v_max3_f32 v0, v0, v162, v163
	v_max3_f32 v10, v10, v146, v147
	v_max3_f32 v0, v0, v164, v165
	v_max3_f32 v10, v10, v148, v149
	v_max3_f32 v0, v0, v166, v167
	v_max3_f32 v10, v10, v150, v151
	v_max3_f32 v0, v0, v168, v169
	v_max3_f32 v10, v10, v152, v153
	v_max3_f32 v0, v0, v170, v171
	v_max3_f32 v10, v10, v154, v155
	v_max3_f32 v0, v0, v172, v173
	v_max3_f32 v10, v10, v156, v157
	v_max3_f32 v0, v0, v174, v175
	v_max3_f32 v10, v10, v158, v159
	v_max_f32_e32 v0, v0, v10
	v_mov_b32_e32 v10, v0
	s_nop 1
	v_permlane32_swap_b32_e32 v0, v10
	v_max_f32_e32 v10, v10, v10
	v_max_f32_e32 v0, v0, v0
	v_max_f32_e32 v10, v0, v10
	v_cmp_lt_f32_e32 vcc, s51, v10
	s_cmp_lg_u64 vcc, 0
	s_cselect_b64 s[22:23], -1, 0
	v_mov_b32_e32 v0, 1.0
	s_cbranch_vccnz .LBB0_731
	s_andn2_b64 vcc, exec, s[22:23]
	s_cbranch_vccz .LBB0_732

; template <int MODE, bool FIRST, bool FOLD>
; __device__ __forceinline__ bool partialSM(f32x16& p0, f32x16& p1, float& m_reg, float& alpha, int relbase, bool near, const float* lut, float cb) {
;     ...
;     float pmax = p0[0];
; #pragma unroll
;     for (int r = 1; r < 16; ++r) pmax = fmaxf(pmax, p0[r]);
; #pragma unroll
;     for (int r = 0; r < 16; ++r) pmax = fmaxf(pmax, p1[r]);
;     { auto rr = __builtin_amdgcn_permlane32_swap(__float_as_uint(pmax), __float_as_uint(pmax), false, false);
;       pmax = fmaxf(__uint_as_float(rr[0]), __uint_as_float(rr[1])); }
;     bool resc;
;     if (FIRST && MODE != 2) resc = true; else resc = __any(pmax > THR2);
.LBB0_726:
	v_max_f32_e32 v2, v161, v161
	v_max_f32_e32 v3, v160, v160
	v_max_f32_e32 v2, v3, v2
	v_max_f32_e32 v3, v128, v129
	v_max3_f32 v2, v2, v162, v163
	v_max3_f32 v3, v3, v130, v131
	v_max3_f32 v2, v2, v164, v165
	v_max3_f32 v3, v3, v132, v133
	v_max3_f32 v2, v2, v166, v167
	v_max3_f32 v3, v3, v134, v135
	v_max3_f32 v2, v2, v168, v169
	v_max3_f32 v3, v3, v136, v137
	v_max3_f32 v2, v2, v170, v171
	v_max3_f32 v3, v3, v138, v139
	v_max3_f32 v2, v2, v172, v173
	v_max3_f32 v3, v3, v140, v141
	v_max3_f32 v2, v2, v174, v175
	v_max3_f32 v3, v3, v142, v143
	v_max_f32_e32 v2, v2, v3
	v_mov_b32_e32 v3, v2
	s_nop 1
	v_permlane32_swap_b32_e32 v2, v3
	v_max_f32_e32 v3, v3, v3
	v_max_f32_e32 v2, v2, v2
	v_max_f32_e32 v3, v2, v3
	v_cmp_lt_f32_e32 vcc, s51, v3
	s_cmp_lg_u64 vcc, 0
	s_cselect_b64 s[20:21], -1, 0
	v_mov_b32_e32 v2, 1.0
	s_cbranch_vccnz .LBB0_736
	s_andn2_b64 vcc, exec, s[20:21]
	s_cbranch_vccz .LBB0_737

; template <int MODE, bool FIRST, bool FOLD>
; __device__ __forceinline__ bool partialSM(f32x16& p0, f32x16& p1, float& m_reg, float& alpha, int relbase, bool near, const float* lut, float cb) {
;     ...
;     float pmax = p0[0];
; #pragma unroll
;     for (int r = 1; r < 16; ++r) pmax = fmaxf(pmax, p0[r]);
; #pragma unroll
;     for (int r = 0; r < 16; ++r) pmax = fmaxf(pmax, p1[r]);
;     { auto rr = __builtin_amdgcn_permlane32_swap(__float_as_uint(pmax), __float_as_uint(pmax), false, false);
;       pmax = fmaxf(__uint_as_float(rr[0]), __uint_as_float(rr[1])); }
;     bool resc;
;     if (FIRST && MODE != 2) resc = true; else resc = __any(pmax > THR2);
.LBB0_786:
	v_max_f32_e32 v0, v145, v145
	v_max_f32_e32 v10, v144, v144
	v_max_f32_e32 v0, v10, v0
	v_max_f32_e32 v10, v128, v129
	v_max3_f32 v0, v0, v146, v147
	v_max3_f32 v10, v10, v130, v131
	v_max3_f32 v0, v0, v148, v149
	v_max3_f32 v10, v10, v132, v133
	v_max3_f32 v0, v0, v150, v151
	v_max3_f32 v10, v10, v134, v135
	v_max3_f32 v0, v0, v152, v153
	v_max3_f32 v10, v10, v136, v137
	v_max3_f32 v0, v0, v154, v155
	v_max3_f32 v10, v10, v138, v139
	v_max3_f32 v0, v0, v156, v157
	v_max3_f32 v10, v10, v140, v141
	v_max3_f32 v0, v0, v158, v159
	v_max3_f32 v10, v10, v142, v143
	v_max_f32_e32 v0, v0, v10
	v_mov_b32_e32 v10, v0
	s_nop 1
	v_permlane32_swap_b32_e32 v0, v10
	v_max_f32_e32 v10, v10, v10
	v_max_f32_e32 v0, v0, v0
	v_max_f32_e32 v10, v0, v10
	v_cmp_lt_f32_e32 vcc, s51, v10
	s_cmp_lg_u64 vcc, 0
	s_cselect_b64 s[14:15], -1, 0
	v_mov_b32_e32 v0, 1.0
	s_cbranch_vccnz .LBB0_806
	s_andn2_b64 vcc, exec, s[14:15]
	s_cbranch_vccz .LBB0_807

; template <int MODE, bool FIRST, bool FOLD>
; __device__ __forceinline__ bool partialSM(f32x16& p0, f32x16& p1, float& m_reg, float& alpha, int relbase, bool near, const float* lut, float cb) {
;     ...
;     float pmax = p0[0];
; #pragma unroll
;     for (int r = 1; r < 16; ++r) pmax = fmaxf(pmax, p0[r]);
; #pragma unroll
;     for (int r = 0; r < 16; ++r) pmax = fmaxf(pmax, p1[r]);
;     { auto rr = __builtin_amdgcn_permlane32_swap(__float_as_uint(pmax), __float_as_uint(pmax), false, false);
;       pmax = fmaxf(__uint_as_float(rr[0]), __uint_as_float(rr[1])); }
;     bool resc;
;     if (FIRST && MODE != 2) resc = true; else resc = __any(pmax > THR2);
.LBB0_801:
	v_max_f32_e32 v2, v145, v145
	v_max_f32_e32 v3, v144, v144
	v_max_f32_e32 v2, v3, v2
	v_max_f32_e32 v3, v112, v113
	v_max3_f32 v2, v2, v146, v147
	v_max3_f32 v3, v3, v114, v115
	v_max3_f32 v2, v2, v148, v149
	v_max3_f32 v3, v3, v116, v117
	v_max3_f32 v2, v2, v150, v151
	v_max3_f32 v3, v3, v118, v119
	v_max3_f32 v2, v2, v152, v153
	v_max3_f32 v3, v3, v120, v121
	v_max3_f32 v2, v2, v154, v155
	v_max3_f32 v3, v3, v122, v123
	v_max3_f32 v2, v2, v156, v157
	v_max3_f32 v3, v3, v124, v125
	v_max3_f32 v2, v2, v158, v159
	v_max3_f32 v3, v3, v126, v127
	v_max_f32_e32 v2, v2, v3
	v_mov_b32_e32 v3, v2
	s_nop 1
	v_permlane32_swap_b32_e32 v2, v3
	v_max_f32_e32 v3, v3, v3
	v_max_f32_e32 v2, v2, v2
	v_max_f32_e32 v3, v2, v3
	v_cmp_lt_f32_e32 vcc, s51, v3
	s_cmp_lg_u64 vcc, 0
	s_cselect_b64 s[12:13], -1, 0
	v_mov_b32_e32 v2, 1.0
	s_cbranch_vccnz .LBB0_811
	s_andn2_b64 vcc, exec, s[12:13]
	s_cbranch_vccz .LBB0_812
